# P5 gMLP u operands via whole-line wave loads (8 rows x 128 B per instruction) and a per-wave LDS hand-off instead of 16-byte row gathers + permlane swaps
# baseline (speedup 1.0000x reference)
; template <bool PASS2>
; __device__ __forceinline__ void s5_tile(const Ctx& C, int T, int sb_lo, int sb_hi, LAS unsigned char* lds, int wave, int lane) {
;     ...
;     for (int gi = 0; gi < 4; ++gi) {
;         const int g = wave * 4 + gi;
;         if (!PASS2) { v2f* Ep = (v2f*)C.E() + ((size_t)T * NG + g) * NP + lane; *Ep = (v2f){sr[gi], si[gi]}; }
; __device__ __forceinline__ void gmlp_tile(const Ctx& C, int T, LAS unsigned char* lds, int wave, int lane, int tid) {
;     ...
;     const bf16* zt = C.Z() + (size_t)(r0 + t) * DIN;
;     const int row = tid >> 2, q = tid & 3;
;     const bf16* vsrc = C.Z() + (size_t)(r0 + row) * DIN + 512 + q * 32;
;     const bf16* Weff = C.Weff();
;     v4u vraw[4];
; #pragma unroll
;     for (int i = 0; i < 4; ++i) vraw[i] = *(const v4u*)(vsrc + 8 * i);
; #pragma unroll
;     for (int h = 0; h < 4; ++h) {
;         bfx8 wf[8];
;         const bf16* wrow = Weff + ((size_t)(mode * 4 + h) * 128 + t) * 128 + 8 * hh;
; #pragma unroll
;         for (int ks = 0; ks < 8; ++ks) wf[ks] = *(const bfx8*)(wrow + 16 * ks);
;         v2u uw[2][4];
; #pragma unroll
;         for (int dbi = 0; dbi < 2; ++dbi)
; #pragma unroll
;             for (int rg = 0; rg < 4; ++rg) uw[dbi][rg] = *(const v2u*)(zt + h * 128 + 32 * (2 * dh + dbi) + 8 * rg + 4 * hh);
.LBB0_599:
	s_mov_b64 s[0:1], s[80:81]
	s_load_dwordx2 s[0:1], s[0:1], 0x110
	s_lshl_b32 s28, s42, 2
	s_ashr_i32 s25, s24, 31
	s_lshl_b64 s[52:53], s[24:25], 14
	s_ashr_i32 s29, s28, 31
	s_waitcnt lgkmcnt(0)
	s_add_u32 s3, s0, s52
	s_addc_u32 s25, s1, s53
	s_lshl_b64 s[0:1], s[28:29], 9
	s_add_u32 s0, s3, s0
	s_addc_u32 s1, s25, s1
	v_lshlrev_b32_e32 v82, 3, v80
	v_lshl_add_u64 v[0:1], s[0:1], 0, v[82:83]
	v_add_co_u32_e32 v0, vcc, s35, v0
	v_pk_mov_b32 v[2:3], v[166:167], v[166:167] op_sel:[1,0]
	s_nop 0
	v_addc_co_u32_e32 v1, vcc, 0, v1, vcc
	s_mov_b64 s[0:1], s[80:81]
	global_store_dwordx2 v[0:1], v[2:3], off
	s_load_dwordx2 s[0:1], s[0:1], 0x110
	s_or_b32 s54, s28, 1
	s_ashr_i32 s55, s54, 31
	v_pk_mov_b32 v[2:3], v[164:165], v[164:165] op_sel:[1,0]
	v_mov_b32_e32 v97, v83
	s_waitcnt lgkmcnt(0)
	s_add_u32 s3, s0, s52
	s_addc_u32 s25, s1, s53
	s_lshl_b64 s[0:1], s[54:55], 9
	s_add_u32 s0, s3, s0
	s_addc_u32 s1, s25, s1
	v_lshl_add_u64 v[0:1], s[0:1], 0, v[82:83]
	v_add_co_u32_e32 v0, vcc, s35, v0
	s_mov_b64 s[0:1], s[80:81]
	s_nop 0
	v_addc_co_u32_e32 v1, vcc, 0, v1, vcc
	global_store_dwordx2 v[0:1], v[2:3], off
	s_load_dwordx2 s[0:1], s[0:1], 0x110
	s_or_b32 s54, s28, 2
	s_ashr_i32 s55, s54, 31
	v_pk_mov_b32 v[2:3], v[162:163], v[162:163] op_sel:[1,0]
	v_mov_b32_e32 v101, v83
	s_waitcnt lgkmcnt(0)
	s_add_u32 s3, s0, s52
	s_addc_u32 s25, s1, s53
	s_lshl_b64 s[0:1], s[54:55], 9
	s_add_u32 s0, s3, s0
	s_addc_u32 s1, s25, s1
	v_lshl_add_u64 v[0:1], s[0:1], 0, v[82:83]
	v_add_co_u32_e32 v0, vcc, s35, v0
	s_mov_b64 s[0:1], s[80:81]
	s_nop 0
	v_addc_co_u32_e32 v1, vcc, 0, v1, vcc
	global_store_dwordx2 v[0:1], v[2:3], off
	s_load_dwordx2 s[0:1], s[0:1], 0x110
	s_or_b32 s28, s28, 3
	s_ashr_i32 s29, s28, 31
	v_pk_mov_b32 v[2:3], v[160:161], v[160:161] op_sel:[1,0]
	v_lshlrev_b32_e32 v139, 2, v86
	s_waitcnt lgkmcnt(0)
	s_add_u32 s3, s0, s52
	s_addc_u32 s25, s1, s53
	s_lshl_b64 s[0:1], s[28:29], 9
	s_add_u32 s0, s3, s0
	s_addc_u32 s1, s25, s1
	v_lshl_add_u64 v[0:1], s[0:1], 0, v[82:83]
	v_add_co_u32_e32 v0, vcc, s35, v0
	s_mov_b64 s[0:1], s[80:81]
	s_nop 0
	v_addc_co_u32_e32 v1, vcc, 0, v1, vcc
	global_store_dwordx2 v[0:1], v[2:3], off
	s_barrier
	s_mov_b64 s[28:29], s[80:81]
	s_load_dwordx2 s[0:1], s[0:1], 0x110
	s_load_dwordx2 s[28:29], s[28:29], 0x110
	v_add_u32_e32 v2, s26, v173
	v_lshlrev_b32_e32 v82, 1, v86
	s_lshl_b32 s3, s42, 5
	s_and_b32 s3, s3, 0x60
	s_waitcnt lgkmcnt(0)
	v_mov_b64_e32 v[0:1], s[28:29]
	v_mad_i64_i32 v[0:1], s[28:29], v2, s34, v[0:1]
	v_lshl_add_u64 v[0:1], v[0:1], 0, v[82:83]
	v_add_co_u32_e32 v2, vcc, s36, v0
	s_mov_b64 s[28:29], s[80:81]
	s_nop 0
	v_addc_co_u32_e32 v3, vcc, 0, v1, vcc
	global_load_dwordx4 v[8:11], v[2:3], off offset:1024
	v_lshl_add_u64 v[108:109], v[0:1], 0, s[18:19]
	global_load_dwordx4 v[12:15], v[108:109], off offset:16
	global_load_dwordx4 v[16:19], v[108:109], off offset:32
	global_load_dwordx4 v[20:23], v[108:109], off offset:48
	v_or_b32_e32 v132, s3, v85
	v_or_b32_e32 v2, s26, v132
	s_load_dwordx2 s[26:27], s[28:29], 0x110
	v_mov_b64_e32 v[0:1], s[0:1]
	s_ashr_i32 s13, s13, 8
	v_mad_i64_i32 v[0:1], s[0:1], v2, s34, v[0:1]
	s_waitcnt lgkmcnt(0)
	v_lshl_add_u64 v[2:3], s[26:27], 0, v[96:97]
	v_lshlrev_b32_e32 v82, 8, v132
	s_lshl_b32 s26, s13, 6
	v_lshl_add_u64 v[104:105], v[2:3], 0, v[82:83]
	v_bfe_u32 v234, v81, 5, 1
	v_mul_u32_u24_e32 v234, 0x1f0, v234
	v_mul_u32_u24_e32 v235, 0xf0, v85
	v_sub_u32_e32 v234, v234, v235
	v_add_u32_e32 v234, 0xe00, v234
	v_ashrrev_i32_e32 v235, 31, v234
	v_lshl_add_u64 v[104:105], v[234:235], 0, v[104:105]
	v_lshl_add_u64 v[4:5], v[0:1], 0, v[100:101]
	v_add_co_u32_e32 v0, vcc, s37, v104
	s_ashr_i32 s27, s26, 31
	v_lshl_add_u64 v[6:7], v[104:105], 0, s[20:21]
	v_addc_co_u32_e32 v1, vcc, 0, v105, vcc
	v_lshl_add_u64 v[4:5], s[26:27], 1, v[4:5]
	global_load_dwordx4 v[64:67], v[6:7], off offset:-2560
	global_load_dwordx4 v[60:63], v[6:7], off offset:-1536
	global_load_dwordx4 v[56:59], v[6:7], off offset:-512
	global_load_dwordx4 v[48:51], v[6:7], off offset:512
	global_load_dwordx4 v[44:47], v[6:7], off offset:1536
	global_load_dwordx4 v[36:39], v[6:7], off offset:2560
	s_nop 0
	global_load_dwordx4 v[0:3], v[0:1], off offset:-3584
	s_nop 0
	global_load_dwordx4 v[28:31], v[6:7], off offset:3584
	v_add_co_u32_e32 v6, vcc, s36, v4
	v_lshl_add_u64 v[106:107], v[4:5], 0, s[22:23]
	v_bfe_u32 v236, v81, 3, 3
	v_mul_u32_u24_e32 v233, 0x90, v236
	v_sub_u32_e32 v236, v236, v85
	v_mul_i32_i24_e32 v236, 0xc00, v236
	v_and_b32_e32 v237, 7, v81
	v_lshlrev_b32_e32 v237, 4, v237
	v_add_u32_e32 v236, v236, v237
	v_add_u32_e32 v233, v233, v237
	v_bfe_u32 v237, v81, 5, 1
	v_lshlrev_b32_e32 v237, 3, v237
	v_sub_u32_e32 v236, v236, v237
	v_lshrrev_b32_e32 v254, 6, v81
	v_mul_u32_u24_e32 v254, 0x1200, v254
	v_add_u32_e32 v254, 0xa000, v254
	v_mul_u32_u24_e32 v255, 0x90, v85
	v_add3_u32 v255, v255, v237, v254
	v_add_u32_e32 v254, v254, v233
	v_ashrrev_i32_e32 v237, 31, v236
	v_lshl_add_u64 v[236:237], v[106:107], 0, v[236:237]
	s_movk_i32 s98, 0x6000
	s_mov_b32 s99, 0
	s_mov_b32 s100, 0xfffee000
	s_mov_b32 s101, -1
	s_nop 0
	v_addc_co_u32_e32 v7, vcc, 0, v5, vcc
	s_mov_b64 s[0:1], s[80:81]
	global_load_dwordx4 v[238:241], v[236:237], off
	v_lshl_add_u64 v[236:237], v[236:237], 0, s[98:99]
	global_load_dwordx4 v[242:245], v[236:237], off
	v_lshl_add_u64 v[236:237], v[236:237], 0, s[98:99]
	global_load_dwordx4 v[246:249], v[236:237], off
	v_lshl_add_u64 v[236:237], v[236:237], 0, s[98:99]
	global_load_dwordx4 v[250:253], v[236:237], off
	v_lshl_add_u64 v[236:237], v[236:237], 0, s[100:101]
	s_nop 0
	s_nop 0
	s_load_dwordx2 s[0:1], s[0:1], 0x68
	v_lshlrev_b32_e32 v156, 2, v132
	v_or_b32_e32 v157, s26, v85
	s_waitcnt lgkmcnt(0)
; __device__ __forceinline__ float bf_lo(unsigned w) { return __uint_as_float(w << 16); }
; __device__ __forceinline__ float bf_hi(unsigned w) { return __uint_as_float(w & 0xffff0000u); }
; __device__ __forceinline__ bf16 f2bf(float f) { return (bf16)(cvt_pk_nv(f, 0.f) & 0xffffu); }
;     __device__ __forceinline__ const float* in(int i) const { return karg_in(i); }
; __device__ __forceinline__ void gmlp_tile(const Ctx& C, int T, LAS unsigned char* lds, int wave, int lane, int tid) {
;     ...
;         const float bias = C.in(13)[h * 128 + (mode ? (t & 15) : t)];
;         v4f gvv[8];
;         { const float* gvp = C.in(11) + h * 128 + q * 32;
; #pragma unroll
;           for (int i = 0; i < 8; ++i) gvv[i] = *(const v4f*)(gvp + 4 * i); }
;         __syncthreads();
;         {
;             float v[32]; float s = 0.f;
; #pragma unroll
;             for (int i = 0; i < 4; ++i) { const v4u w = vraw[i];
;                 v[8 * i + 0] = bf_lo(w.x); v[8 * i + 1] = bf_hi(w.x); v[8 * i + 2] = bf_lo(w.y); v[8 * i + 3] = bf_hi(w.y);
;                 v[8 * i + 4] = bf_lo(w.z); v[8 * i + 5] = bf_hi(w.z); v[8 * i + 6] = bf_lo(w.w); v[8 * i + 7] = bf_hi(w.w); }
;             if (h < 3) {
; #pragma unroll
;                 for (int i = 0; i < 4; ++i) vraw[i] = *(const v4u*)(vsrc + (h + 1) * 128 + 8 * i);
;             }
; #pragma unroll
;             for (int i = 0; i < 32; ++i) s += v[i] * v[i];
;             s += __shfl_xor(s, 1); s += __shfl_xor(s, 2);
;             const float r = rsqrtf(s * (1.f / 128.f) + EPS);
; #pragma unroll
;             for (int i = 0; i < 32; ++i) { v[i] = v[i] * r * gvv[i >> 2][i & 3]; VT[(q * 32 + i) * VT_STRIDE + row] = f2bf(v[i]); }
	global_load_dword v128, v156, s[0:1]
	s_mov_b64 s[0:1], s[80:81]
	s_load_dwordx2 s[28:29], s[0:1], 0x58
	s_waitcnt lgkmcnt(0)
	global_load_dwordx4 v[114:117], v139, s[28:29] offset:48
	global_load_dwordx4 v[118:121], v139, s[28:29] offset:32
	global_load_dwordx4 v[122:125], v139, s[28:29] offset:16
	global_load_dwordx4 v[134:137], v139, s[28:29]
	s_waitcnt vmcnt(20)
	v_and_b32_e32 v97, 0xffff0000, v8
	v_lshlrev_b32_e32 v82, 16, v8
	v_lshlrev_b32_e32 v130, 16, v10
	v_and_b32_e32 v131, 0xffff0000, v10
	v_mul_f32_e32 v10, v97, v97
	v_lshlrev_b32_e32 v101, 16, v9
	v_fmac_f32_e32 v10, v82, v82
	v_and_b32_e32 v129, 0xffff0000, v9
	v_fmac_f32_e32 v10, v101, v101
	v_fmac_f32_e32 v10, v129, v129
	v_fmac_f32_e32 v10, v130, v130
	v_lshlrev_b32_e32 v133, 16, v11
	v_fmac_f32_e32 v10, v131, v131
	v_and_b32_e32 v138, 0xffff0000, v11
	v_fmac_f32_e32 v10, v133, v133
	s_waitcnt vmcnt(19)
	v_lshlrev_b32_e32 v140, 16, v12
	v_fmac_f32_e32 v10, v138, v138
	v_and_b32_e32 v141, 0xffff0000, v12
	v_fmac_f32_e32 v10, v140, v140
	v_lshlrev_b32_e32 v142, 16, v13
	v_fmac_f32_e32 v10, v141, v141
	v_and_b32_e32 v143, 0xffff0000, v13
	v_fmac_f32_e32 v10, v142, v142
	v_lshlrev_b32_e32 v144, 16, v14
	v_fmac_f32_e32 v10, v143, v143
	v_and_b32_e32 v145, 0xffff0000, v14
	v_fmac_f32_e32 v10, v144, v144
	v_lshlrev_b32_e32 v146, 16, v15
	v_fmac_f32_e32 v10, v145, v145
	v_and_b32_e32 v147, 0xffff0000, v15
	v_fmac_f32_e32 v10, v146, v146
	s_waitcnt vmcnt(18)
	v_lshlrev_b32_e32 v148, 16, v16
	v_fmac_f32_e32 v10, v147, v147
	v_and_b32_e32 v149, 0xffff0000, v16
	v_fmac_f32_e32 v10, v148, v148
	v_lshlrev_b32_e32 v150, 16, v17
	v_fmac_f32_e32 v10, v149, v149
	v_and_b32_e32 v151, 0xffff0000, v17
	v_fmac_f32_e32 v10, v150, v150
	v_lshlrev_b32_e32 v152, 16, v18
	v_fmac_f32_e32 v10, v151, v151
	v_and_b32_e32 v153, 0xffff0000, v18
	v_fmac_f32_e32 v10, v152, v152
	v_lshlrev_b32_e32 v154, 16, v19
	v_fmac_f32_e32 v10, v153, v153
	v_and_b32_e32 v155, 0xffff0000, v19
	v_fmac_f32_e32 v10, v154, v154
	s_waitcnt vmcnt(17)
	v_and_b32_e32 v74, 0xffff0000, v20
	v_lshlrev_b32_e32 v75, 16, v20
	v_fmac_f32_e32 v10, v155, v155
	v_pk_mul_f32 v[8:9], v[74:75], v[74:75]
	v_and_b32_e32 v102, 0xffff0000, v21
	v_add_f32_e32 v9, v9, v10
	v_lshlrev_b32_e32 v103, 16, v21
	v_add_f32_e32 v10, v8, v9
	v_pk_mul_f32 v[8:9], v[102:103], v[102:103]
	v_and_b32_e32 v110, 0xffff0000, v22
	v_add_f32_e32 v9, v9, v10
	v_lshlrev_b32_e32 v111, 16, v22
	v_add_f32_e32 v10, v8, v9
	v_pk_mul_f32 v[8:9], v[110:111], v[110:111]
	v_and_b32_e32 v126, 0xffff0000, v23
	v_add_f32_e32 v9, v9, v10
	v_lshlrev_b32_e32 v127, 16, v23
	v_add_f32_e32 v10, v8, v9
	v_pk_mul_f32 v[8:9], v[126:127], v[126:127]
	s_nop 0
	v_add_f32_e32 v9, v9, v10
	v_add_f32_e32 v16, v8, v9
	ds_bpermute_b32 v17, v183, v16
	global_load_dwordx4 v[8:11], v139, s[28:29] offset:112
	global_load_dwordx4 v[12:15], v139, s[28:29] offset:96
	s_waitcnt lgkmcnt(0)
	v_add_f32_e32 v24, v16, v17
	global_load_dwordx4 v[16:19], v139, s[28:29] offset:80
	global_load_dwordx4 v[20:23], v139, s[28:29] offset:64
	ds_bpermute_b32 v25, v184, v24
	s_waitcnt lgkmcnt(0)
	s_barrier
	v_add_f32_e32 v24, v24, v25
	v_fmamk_f32 v24, v24, 0x3c000000, v177
	v_mul_f32_e32 v25, 0x4b800000, v24
	v_cmp_gt_f32_e32 vcc, s38, v24
	s_nop 1
	v_cndmask_b32_e32 v24, v24, v25, vcc
	v_rsq_f32_e32 v158, v24
	global_load_dwordx4 v[24:27], v[108:109], off offset:304
	global_load_dwordx4 v[32:35], v[108:109], off offset:288
	global_load_dwordx4 v[40:43], v[108:109], off offset:272
	global_load_dwordx4 v[52:55], v[108:109], off offset:256
	v_mul_f32_e32 v159, 0x45800000, v158
	v_cndmask_b32_e32 v158, v158, v159, vcc
	v_mul_f32_e32 v82, v158, v82
	s_waitcnt vmcnt(8)
	ds_write_b128 v254, v[238:241]
	ds_write_b128 v254, v[242:245] offset:1152
	ds_write_b128 v254, v[246:249] offset:2304
	ds_write_b128 v254, v[250:253] offset:3456
	s_waitcnt lgkmcnt(0)
	ds_read_b64 v[6:7], v255
	ds_read_b64 v[4:5], v255 offset:16
	ds_read_b64 v[72:73], v255 offset:32
	ds_read_b64 v[70:71], v255 offset:48
	ds_read_b64 v[68:69], v255 offset:64
	ds_read_b64 v[112:113], v255 offset:80
	ds_read_b64 v[78:79], v255 offset:96
	ds_read_b64 v[76:77], v255 offset:112
	s_waitcnt lgkmcnt(0)
	v_mul_f32_e32 v82, v134, v82
	v_cvt_pk_bf16_f32 v82, v82, v83
	ds_write_b16 v174, v82
	v_mul_f32_e32 v82, v158, v97
	v_mul_f32_e32 v82, v135, v82
	v_cvt_pk_bf16_f32 v82, v82, v83
	ds_write_b16 v174, v82 offset:272
	v_mul_f32_e32 v82, v158, v101
	v_mul_f32_e32 v82, v136, v82
	v_cvt_pk_bf16_f32 v82, v82, v83
	ds_write_b16 v174, v82 offset:544
	v_mul_f32_e32 v82, v158, v129
	v_mul_f32_e32 v82, v137, v82
	v_cvt_pk_bf16_f32 v82, v82, v83
	ds_write_b16 v174, v82 offset:816
	v_mul_f32_e32 v82, v158, v130
	v_mul_f32_e32 v82, v122, v82
	v_cvt_pk_bf16_f32 v82, v82, v83
	ds_write_b16 v174, v82 offset:1088
	v_mul_f32_e32 v82, v158, v131
	v_mul_f32_e32 v82, v123, v82
	v_cvt_pk_bf16_f32 v82, v82, v83
	ds_write_b16 v174, v82 offset:1360
	v_mul_f32_e32 v82, v158, v133
	v_mul_f32_e32 v82, v124, v82
	v_cvt_pk_bf16_f32 v82, v82, v83
	ds_write_b16 v174, v82 offset:1632
	v_mul_f32_e32 v82, v158, v138
	v_mul_f32_e32 v82, v125, v82
	v_cvt_pk_bf16_f32 v82, v82, v83
	ds_write_b16 v174, v82 offset:1904
	v_mul_f32_e32 v82, v158, v140
	v_mul_f32_e32 v82, v118, v82
	v_cvt_pk_bf16_f32 v82, v82, v83
	ds_write_b16 v174, v82 offset:2176
	v_mul_f32_e32 v82, v158, v141
	v_mul_f32_e32 v82, v119, v82
	v_cvt_pk_bf16_f32 v82, v82, v83
	ds_write_b16 v174, v82 offset:2448
	v_mul_f32_e32 v82, v158, v142
	v_mul_f32_e32 v82, v120, v82
	v_cvt_pk_bf16_f32 v82, v82, v83
	ds_write_b16 v174, v82 offset:2720
	v_mul_f32_e32 v82, v158, v143
	v_mul_f32_e32 v82, v121, v82
	v_cvt_pk_bf16_f32 v82, v82, v83
	ds_write_b16 v174, v82 offset:2992
	v_mul_f32_e32 v82, v158, v144
	v_mul_f32_e32 v82, v114, v82
	v_cvt_pk_bf16_f32 v82, v82, v83
	ds_write_b16 v174, v82 offset:3264
	v_mul_f32_e32 v82, v158, v145
	v_mul_f32_e32 v82, v115, v82
	v_cvt_pk_bf16_f32 v82, v82, v83
	ds_write_b16 v174, v82 offset:3536
	v_mul_f32_e32 v82, v158, v146
	v_mul_f32_e32 v82, v116, v82
	v_cvt_pk_bf16_f32 v82, v82, v83
	ds_write_b16 v174, v82 offset:3808
	v_mul_f32_e32 v82, v158, v147
	v_mul_f32_e32 v82, v117, v82
	v_cvt_pk_bf16_f32 v82, v82, v83
	ds_write_b16 v174, v82 offset:4080
	v_mul_f32_e32 v82, v158, v148
	s_waitcnt vmcnt(4)
; __device__ __forceinline__ float bf_lo(unsigned w) { return __uint_as_float(w << 16); }
; __device__ __forceinline__ float bf_hi(unsigned w) { return __uint_as_float(w & 0xffff0000u); }
; #define LAS __attribute__((address_space(3)))
; __device__ __forceinline__ unsigned cvt_pk_nv(float lo, float hi) { unsigned r; asm("v_cvt_pk_bf16_f32 %0, %1, %2" : "=v"(r) : "v"(lo), "v"(hi)); return r; }
; __device__ __forceinline__ bf16 f2bf(float f) { return (bf16)(cvt_pk_nv(f, 0.f) & 0xffffu); }
;     __device__ __forceinline__ float* out() const { return (float*)karg_in(33); }
; __device__ __forceinline__ void gmlp_tile(const Ctx& C, int T, LAS unsigned char* lds, int wave, int lane, int tid) {
;     ...
;             for (int i = 0; i < 32; ++i) { v[i] = v[i] * r * gvv[i >> 2][i & 3]; VT[(q * 32 + i) * VT_STRIDE + row] = f2bf(v[i]); }
;             if (mode) { float* ov = C.out() + OFF_V_S + (size_t)row * AW + h * 128 + q * 32;
; #pragma unroll
;                 for (int i = 0; i < 8; ++i) *(v4f*)(ov + 4 * i) = (v4f){v[4 * i], v[4 * i + 1], v[4 * i + 2], v[4 * i + 3]}; }
;         }
;         __syncthreads();
; #pragma unroll
;         for (int dbi = 0; dbi < 2; ++dbi) {
;             const int db = 2 * dh + dbi;
;             v16f acc;
; #pragma unroll
;             for (int r = 0; r < 16; ++r) acc[r] = 0.f;
; #pragma unroll
;             for (int ks = 0; ks < 8; ++ks) {
;                 const bfx8 va = *(const LAS bfx8*)(VT + (32 * db + tl) * VT_STRIDE + 16 * ks + 8 * hh);
;                 acc = __builtin_amdgcn_mfma_f32_32x32x16_bf16(va, wf[ks], acc, 0, 0, 0);
;             }
; #pragma unroll
;             for (int rg = 0; rg < 4; ++rg) {
;                 const v2u u2 = uw[dbi][rg];
;                 const float o0 = bf_lo(u2.x) * (acc[4 * rg + 0] + bias), o1 = bf_hi(u2.x) * (acc[4 * rg + 1] + bias);
;                 const float o2 = bf_lo(u2.y) * (acc[4 * rg + 2] + bias), o3 = bf_hi(u2.y) * (acc[4 * rg + 3] + bias);
;                 ssq += (o0 * o0 + o1 * o1) + (o2 * o2 + o3 * o3);
;                 outp[h][dbi][2 * rg] = cvt_pk_nv(o0, o1); outp[h][dbi][2 * rg + 1] = cvt_pk_nv(o2, o3);
;             }
	v_mul_f32_e32 v20, v20, v82
	v_cvt_pk_bf16_f32 v20, v20, v83
	ds_write_b16 v174, v20 offset:4352
	v_mul_f32_e32 v20, v158, v149
	v_mul_f32_e32 v20, v21, v20
	v_cvt_pk_bf16_f32 v20, v20, v83
	ds_write_b16 v174, v20 offset:4624
	v_mul_f32_e32 v20, v158, v150
	v_mul_f32_e32 v20, v22, v20
	v_cvt_pk_bf16_f32 v20, v20, v83
	ds_write_b16 v174, v20 offset:4896
	v_mul_f32_e32 v20, v158, v151
	v_mul_f32_e32 v20, v23, v20
	v_cvt_pk_bf16_f32 v20, v20, v83
	ds_write_b16 v174, v20 offset:5168
	v_mul_f32_e32 v20, v158, v152
	v_mul_f32_e32 v16, v16, v20
	v_cvt_pk_bf16_f32 v16, v16, v83
	ds_write_b16 v174, v16 offset:5440
	v_mul_f32_e32 v16, v158, v153
	v_mul_f32_e32 v16, v17, v16
	v_cvt_pk_bf16_f32 v16, v16, v83
	ds_write_b16 v174, v16 offset:5712
	v_mul_f32_e32 v16, v158, v154
	v_mul_f32_e32 v16, v18, v16
	v_cvt_pk_bf16_f32 v16, v16, v83
	ds_write_b16 v174, v16 offset:5984
	v_mul_f32_e32 v16, v158, v155
	v_mul_f32_e32 v16, v19, v16
	v_cvt_pk_bf16_f32 v16, v16, v83
	ds_write_b16 v174, v16 offset:6256
	v_mul_f32_e32 v16, v158, v75
	v_mul_f32_e32 v12, v12, v16
	v_cvt_pk_bf16_f32 v12, v12, v83
	ds_write_b16 v174, v12 offset:6528
	v_mul_f32_e32 v12, v158, v74
	v_mul_f32_e32 v12, v13, v12
	v_cvt_pk_bf16_f32 v12, v12, v83
	ds_write_b16 v174, v12 offset:6800
	v_mul_f32_e32 v12, v158, v103
	v_mul_f32_e32 v12, v14, v12
	v_cvt_pk_bf16_f32 v12, v12, v83
	ds_write_b16 v174, v12 offset:7072
	v_mul_f32_e32 v12, v158, v102
	v_mul_f32_e32 v12, v15, v12
	v_cvt_pk_bf16_f32 v12, v12, v83
	ds_write_b16 v174, v12 offset:7344
	v_mul_f32_e32 v12, v158, v111
	v_mul_f32_e32 v8, v8, v12
	v_cvt_pk_bf16_f32 v8, v8, v83
	ds_write_b16 v174, v8 offset:7616
	v_mul_f32_e32 v8, v158, v110
	v_mul_f32_e32 v8, v9, v8
	v_cvt_pk_bf16_f32 v8, v8, v83
	ds_write_b16 v174, v8 offset:7888
	v_mul_f32_e32 v8, v158, v127
	v_mul_f32_e32 v8, v10, v8
	v_cvt_pk_bf16_f32 v8, v8, v83
	ds_write_b16 v174, v8 offset:8160
	v_mul_f32_e32 v8, v158, v126
	v_mul_f32_e32 v8, v11, v8
	v_cvt_pk_bf16_f32 v8, v8, v83
	v_mad_u64_u32 v[102:103], s[0:1], v157, s30, v[90:91]
	ds_write_b16 v174, v8 offset:8432
	s_waitcnt lgkmcnt(0)
	s_barrier
	ds_read_b128 v[8:11], v102
	ds_read_b128 v[114:117], v102 offset:32
	s_waitcnt lgkmcnt(1)
	v_mfma_f32_32x32x16_bf16 v[8:23], v[8:11], v[0:3], 0
	v_lshlrev_b32_e32 v74, 16, v6
	v_and_b32_e32 v6, 0xffff0000, v6
	s_mov_b64 s[0:1], s[80:81]
	s_waitcnt vmcnt(0)
	v_and_b32_e32 v164, 0xffff0000, v52
	v_lshlrev_b32_e32 v158, 16, v52
	v_lshlrev_b32_e32 v200, 16, v34
	v_and_b32_e32 v201, 0xffff0000, v34
	s_waitcnt lgkmcnt(0)
	v_mfma_f32_32x32x16_bf16 v[8:23], v[114:117], v[64:67], v[8:23]
	ds_read_b128 v[114:117], v102 offset:64
	ds_read_b128 v[118:121], v102 offset:96
	v_mul_f32_e32 v34, v164, v164
	v_lshlrev_b32_e32 v165, 16, v53
	v_fmac_f32_e32 v34, v158, v158
	v_and_b32_e32 v166, 0xffff0000, v53
	v_fmac_f32_e32 v34, v165, v165
	v_lshlrev_b32_e32 v167, 16, v54
	s_waitcnt lgkmcnt(1)
	v_mfma_f32_32x32x16_bf16 v[8:23], v[114:117], v[60:63], v[8:23]
	v_fmac_f32_e32 v34, v166, v166
	v_and_b32_e32 v178, 0xffff0000, v54
	v_fmac_f32_e32 v34, v167, v167
	v_lshlrev_b32_e32 v179, 16, v55
	v_fmac_f32_e32 v34, v178, v178
	v_and_b32_e32 v180, 0xffff0000, v55
	v_fmac_f32_e32 v34, v179, v179
	s_waitcnt lgkmcnt(0)
	v_mfma_f32_32x32x16_bf16 v[8:23], v[118:121], v[56:59], v[8:23]
	ds_read_b128 v[114:117], v102 offset:128
	ds_read_b128 v[118:121], v102 offset:160
	v_lshlrev_b32_e32 v181, 16, v40
	v_fmac_f32_e32 v34, v180, v180
	v_and_b32_e32 v189, 0xffff0000, v40
	v_fmac_f32_e32 v34, v181, v181
	v_lshlrev_b32_e32 v190, 16, v41
	v_fmac_f32_e32 v34, v189, v189
	s_waitcnt lgkmcnt(1)
	v_mfma_f32_32x32x16_bf16 v[8:23], v[114:117], v[48:51], v[8:23]
	v_and_b32_e32 v191, 0xffff0000, v41
	v_fmac_f32_e32 v34, v190, v190
	v_lshlrev_b32_e32 v192, 16, v42
	v_fmac_f32_e32 v34, v191, v191
	v_and_b32_e32 v193, 0xffff0000, v42
	v_fmac_f32_e32 v34, v192, v192
	v_lshlrev_b32_e32 v194, 16, v43
	s_waitcnt lgkmcnt(0)
	v_mfma_f32_32x32x16_bf16 v[8:23], v[118:121], v[44:47], v[8:23]
	ds_read_b128 v[114:117], v102 offset:192
	ds_read_b128 v[118:121], v102 offset:224
	v_fmac_f32_e32 v34, v193, v193
	v_and_b32_e32 v195, 0xffff0000, v43
	v_fmac_f32_e32 v34, v194, v194
	v_lshlrev_b32_e32 v196, 16, v32
	v_fmac_f32_e32 v34, v195, v195
	v_and_b32_e32 v197, 0xffff0000, v32
	s_waitcnt lgkmcnt(1)
	v_mfma_f32_32x32x16_bf16 v[8:23], v[114:117], v[36:39], v[8:23]
	ds_read_b128 v[114:117], v102 offset:8736
	v_fmac_f32_e32 v34, v196, v196
	v_lshlrev_b32_e32 v198, 16, v33
	v_fmac_f32_e32 v34, v197, v197
	v_and_b32_e32 v199, 0xffff0000, v33
	v_fmac_f32_e32 v34, v198, v198
	v_fmac_f32_e32 v34, v199, v199
	s_waitcnt lgkmcnt(1)
	v_mfma_f32_32x32x16_bf16 v[8:23], v[118:121], v[28:31], v[8:23]
	ds_read_b128 v[118:121], v102 offset:8768
	v_fmac_f32_e32 v34, v200, v200
	v_lshlrev_b32_e32 v202, 16, v35
	v_fmac_f32_e32 v34, v201, v201
	v_and_b32_e32 v203, 0xffff0000, v35
	v_fmac_f32_e32 v34, v202, v202
	v_fmac_f32_e32 v34, v203, v203
	s_nop 4
	v_add_f32_e32 v9, v128, v9
	v_mul_f32_e32 v6, v9, v6
	v_lshlrev_b32_e32 v9, 16, v7
	v_add_f32_e32 v10, v128, v10
	v_mul_f32_e32 v9, v10, v9
	v_and_b32_e32 v7, 0xffff0000, v7
	v_add_f32_e32 v10, v128, v11
	v_add_f32_e32 v8, v128, v8
	v_mul_f32_e32 v7, v10, v7
	v_mul_f32_e32 v8, v8, v74
	v_mul_f32_e32 v10, v6, v6
	v_mul_f32_e32 v11, v7, v7
	v_cvt_pk_bf16_f32 v97, v8, v6
	v_cvt_pk_bf16_f32 v82, v9, v7
	v_lshlrev_b32_e32 v6, 16, v4
	v_add_f32_e32 v7, v128, v12
	v_mul_f32_e32 v75, v7, v6
	v_and_b32_e32 v4, 0xffff0000, v4
	v_add_f32_e32 v6, v128, v13
	v_mul_f32_e32 v101, v6, v4
	v_lshlrev_b32_e32 v4, 16, v5
	v_add_f32_e32 v6, v128, v14
	v_fmac_f32_e32 v10, v8, v8
	v_mul_f32_e32 v103, v6, v4
	v_and_b32_e32 v8, 0xffff0000, v5
	ds_read_b128 v[4:7], v102 offset:8704
	v_fmac_f32_e32 v11, v9, v9
	v_add_f32_e32 v9, v128, v15
	v_mul_f32_e32 v110, v9, v8
	v_mul_f32_e32 v8, v101, v101
	v_mul_f32_e32 v9, v110, v110
	v_fmac_f32_e32 v8, v75, v75
	v_fmac_f32_e32 v9, v103, v103
	v_add_f32_e32 v74, v10, v11
	v_add_f32_e32 v111, v8, v9
	s_waitcnt lgkmcnt(0)
; __device__ __forceinline__ float bf_lo(unsigned w) { return __uint_as_float(w << 16); }
; __device__ __forceinline__ float bf_hi(unsigned w) { return __uint_as_float(w & 0xffff0000u); }
; #define LAS __attribute__((address_space(3)))
; __device__ __forceinline__ unsigned cvt_pk_nv(float lo, float hi) { unsigned r; asm("v_cvt_pk_bf16_f32 %0, %1, %2" : "=v"(r) : "v"(lo), "v"(hi)); return r; }
;     __device__ __forceinline__ const float* in(int i) const { return karg_in(i); }
; __device__ __forceinline__ void gmlp_tile(const Ctx& C, int T, LAS unsigned char* lds, int wave, int lane, int tid) {
;     ...
;         const bf16* wrow = Weff + ((size_t)(mode * 4 + h) * 128 + t) * 128 + 8 * hh;
; #pragma unroll
;         for (int ks = 0; ks < 8; ++ks) wf[ks] = *(const bfx8*)(wrow + 16 * ks);
;         v2u uw[2][4];
; #pragma unroll
;         for (int dbi = 0; dbi < 2; ++dbi)
; #pragma unroll
;             for (int rg = 0; rg < 4; ++rg) uw[dbi][rg] = *(const v2u*)(zt + h * 128 + 32 * (2 * dh + dbi) + 8 * rg + 4 * hh);
;         const float bias = C.in(13)[h * 128 + (mode ? (t & 15) : t)];
;         v4f gvv[8];
;         { const float* gvp = C.in(11) + h * 128 + q * 32;
; #pragma unroll
;           for (int i = 0; i < 8; ++i) gvv[i] = *(const v4f*)(gvp + 4 * i); }
;     ...
;             for (int ks = 0; ks < 8; ++ks) {
;                 const bfx8 va = *(const LAS bfx8*)(VT + (32 * db + tl) * VT_STRIDE + 16 * ks + 8 * hh);
;                 acc = __builtin_amdgcn_mfma_f32_32x32x16_bf16(va, wf[ks], acc, 0, 0, 0);
;             }
; #pragma unroll
;             for (int rg = 0; rg < 4; ++rg) {
;                 const v2u u2 = uw[dbi][rg];
;                 const float o0 = bf_lo(u2.x) * (acc[4 * rg + 0] + bias), o1 = bf_hi(u2.x) * (acc[4 * rg + 1] + bias);
;                 const float o2 = bf_lo(u2.y) * (acc[4 * rg + 2] + bias), o3 = bf_hi(u2.y) * (acc[4 * rg + 3] + bias);
;                 ssq += (o0 * o0 + o1 * o1) + (o2 * o2 + o3 * o3);
;                 outp[h][dbi][2 * rg] = cvt_pk_nv(o0, o1); outp[h][dbi][2 * rg + 1] = cvt_pk_nv(o2, o3);
;             }
	v_mfma_f32_32x32x16_bf16 v[0:15], v[4:7], v[0:3], 0
	v_cvt_pk_bf16_f32 v134, v75, v101
	v_lshlrev_b32_e32 v75, 16, v72
	v_add_f32_e32 v16, v128, v16
	v_mul_f32_e32 v75, v16, v75
	v_and_b32_e32 v16, 0xffff0000, v72
	v_add_f32_e32 v17, v128, v17
	v_mul_f32_e32 v72, v17, v16
	v_mfma_f32_32x32x16_bf16 v[0:15], v[114:117], v[64:67], v[0:15]
	ds_read_b128 v[64:67], v102 offset:8800
	v_lshlrev_b32_e32 v16, 16, v73
	v_add_f32_e32 v17, v128, v18
	v_mul_f32_e32 v101, v17, v16
	v_and_b32_e32 v16, 0xffff0000, v73
	v_add_f32_e32 v17, v128, v19
	v_add_f32_e32 v74, v74, v111
	v_mfma_f32_32x32x16_bf16 v[0:15], v[118:121], v[60:63], v[0:15]
	v_mul_f32_e32 v60, v17, v16
	ds_read_b128 v[16:19], v102 offset:8832
	v_mul_f32_e32 v61, v72, v72
	v_mul_f32_e32 v62, v60, v60
	v_fmac_f32_e32 v61, v75, v75
	v_fmac_f32_e32 v62, v101, v101
	v_cvt_pk_bf16_f32 v135, v101, v60
	s_waitcnt lgkmcnt(1)
	v_mfma_f32_32x32x16_bf16 v[0:15], v[64:67], v[56:59], v[0:15]
	v_add_f32_e32 v56, v61, v62
	v_add_f32_e32 v61, v56, v74
	ds_read_b128 v[56:59], v102 offset:8864
	v_lshlrev_b32_e32 v60, 16, v70
	v_cvt_pk_bf16_f32 v133, v103, v110
	v_cvt_pk_bf16_f32 v136, v75, v72
	v_and_b32_e32 v130, 0xffff0000, v25
	s_waitcnt lgkmcnt(1)
	v_mfma_f32_32x32x16_bf16 v[0:15], v[16:19], v[48:51], v[0:15]
	v_add_f32_e32 v16, v128, v20
	v_mul_f32_e32 v48, v16, v60
	v_and_b32_e32 v16, 0xffff0000, v70
	v_add_f32_e32 v17, v128, v21
	v_mul_f32_e32 v49, v17, v16
	ds_read_b128 v[16:19], v102 offset:8896
	v_lshlrev_b32_e32 v20, 16, v71
	s_waitcnt lgkmcnt(1)
	v_mfma_f32_32x32x16_bf16 v[0:15], v[56:59], v[44:47], v[0:15]
	v_add_f32_e32 v21, v128, v22
	v_mul_f32_e32 v44, v21, v20
	v_and_b32_e32 v20, 0xffff0000, v71
	v_add_f32_e32 v21, v128, v23
	v_mul_f32_e32 v45, v21, v20
	ds_read_b128 v[20:23], v102 offset:8928
	v_mul_f32_e32 v46, v49, v49
	s_waitcnt lgkmcnt(1)
	v_mfma_f32_32x32x16_bf16 v[0:15], v[16:19], v[36:39], v[0:15]
	v_lshlrev_b32_e32 v17, 16, v68
	v_mul_f32_e32 v16, v45, v45
	v_fmac_f32_e32 v46, v48, v48
	v_fmac_f32_e32 v16, v44, v44
	v_add_f32_e32 v16, v46, v16
	v_add_f32_e32 v16, v16, v61
	v_cvt_pk_bf16_f32 v138, v48, v49
	s_waitcnt lgkmcnt(0)
	v_mfma_f32_32x32x16_bf16 v[0:15], v[20:23], v[28:31], v[0:15]
	v_cvt_pk_bf16_f32 v137, v44, v45
	v_lshlrev_b32_e32 v131, 16, v25
	v_and_b32_e32 v160, 0xffff0000, v26
	v_lshlrev_b32_e32 v161, 16, v26
	v_and_b32_e32 v162, 0xffff0000, v27
	v_lshlrev_b32_e32 v163, 16, v27
	v_lshlrev_b32_e32 v60, 16, v113
	s_nop 5
	v_add_f32_e32 v0, v128, v0
	v_mul_f32_e32 v0, v0, v17
	v_and_b32_e32 v17, 0xffff0000, v68
	v_add_f32_e32 v1, v128, v1
	v_mul_f32_e32 v1, v1, v17
	v_lshlrev_b32_e32 v17, 16, v69
	v_add_f32_e32 v2, v128, v2
	v_mul_f32_e32 v2, v2, v17
	v_and_b32_e32 v17, 0xffff0000, v69
	v_add_f32_e32 v3, v128, v3
	v_mul_f32_e32 v3, v3, v17
	v_mul_f32_e32 v17, v1, v1
	v_mul_f32_e32 v18, v3, v3
	v_fmac_f32_e32 v17, v0, v0
	v_fmac_f32_e32 v18, v2, v2
	v_add_f32_e32 v17, v17, v18
	v_add_f32_e32 v129, v16, v17
	v_add_co_u32_e32 v16, vcc, s39, v104
	v_cvt_pk_bf16_f32 v103, v0, v1
	v_cvt_pk_bf16_f32 v101, v2, v3
	v_add_f32_e32 v4, v128, v4
	s_nop 0
	v_addc_co_u32_e32 v17, vcc, 0, v105, vcc
	global_load_dwordx4 v[0:3], v[16:17], off offset:-3584
	global_load_dwordx4 v[72:75], v[16:17], off offset:-2560
	global_load_dwordx4 v[68:71], v[16:17], off offset:-1536
	global_load_dwordx4 v[64:67], v[16:17], off offset:-512
	global_load_dwordx4 v[56:59], v[16:17], off offset:512
	global_load_dwordx4 v[48:51], v[16:17], off offset:1536
	global_load_dwordx4 v[44:47], v[16:17], off offset:2560
	global_load_dwordx4 v[36:39], v[16:17], off offset:3584
	global_load_dwordx4 v[238:241], v[236:237], off offset:256
	v_lshl_add_u64 v[236:237], v[236:237], 0, s[98:99]
	global_load_dwordx4 v[242:245], v[236:237], off offset:256
	v_lshl_add_u64 v[236:237], v[236:237], 0, s[98:99]
	global_load_dwordx4 v[246:249], v[236:237], off offset:256
	v_lshl_add_u64 v[236:237], v[236:237], 0, s[98:99]
	global_load_dwordx4 v[250:253], v[236:237], off offset:256
	v_lshl_add_u64 v[236:237], v[236:237], 0, s[100:101]
	s_load_dwordx2 s[0:1], s[0:1], 0x68
	v_lshlrev_b32_e32 v16, 16, v112
	v_mul_f32_e32 v157, v4, v16
	v_and_b32_e32 v4, 0xffff0000, v112
	v_add_f32_e32 v5, v128, v5
	s_waitcnt lgkmcnt(0)
	global_load_dword v159, v156, s[0:1] offset:512
	s_mov_b64 s[0:1], s[80:81]
	s_load_dwordx2 s[28:29], s[0:1], 0x58
	s_waitcnt lgkmcnt(0)
	global_load_dwordx4 v[16:19], v139, s[28:29] offset:560
	global_load_dwordx4 v[20:23], v139, s[28:29] offset:544
	global_load_dwordx4 v[28:31], v139, s[28:29] offset:528
	global_load_dwordx4 v[140:143], v139, s[28:29] offset:512
	v_mul_f32_e32 v112, v5, v4
	v_and_b32_e32 v4, 0xffff0000, v24
	v_lshlrev_b32_e32 v5, 16, v24
	v_pk_mul_f32 v[32:33], v[4:5], v[4:5]
	v_add_f32_e32 v6, v128, v6
	v_add_f32_e32 v24, v33, v34
	v_add_f32_e32 v32, v32, v24
	v_pk_mul_f32 v[24:25], v[130:131], v[130:131]
	v_mul_f32_e32 v204, v6, v60
	v_add_f32_e32 v25, v25, v32
	v_add_f32_e32 v32, v24, v25
	v_pk_mul_f32 v[24:25], v[160:161], v[160:161]
	v_and_b32_e32 v6, 0xffff0000, v113
	v_add_f32_e32 v25, v25, v32
	v_add_f32_e32 v26, v24, v25
	v_pk_mul_f32 v[24:25], v[162:163], v[162:163]
	v_add_f32_e32 v8, v128, v8
	v_add_f32_e32 v25, v25, v26
	v_add_f32_e32 v32, v24, v25
	global_load_dwordx4 v[24:27], v139, s[28:29] offset:624
	global_load_dwordx4 v[144:147], v139, s[28:29] offset:608
	global_load_dwordx4 v[148:151], v139, s[28:29] offset:592
	global_load_dwordx4 v[152:155], v139, s[28:29] offset:576
	ds_bpermute_b32 v33, v183, v32
	s_waitcnt lgkmcnt(0)
	s_barrier
; __device__ __forceinline__ float bf_lo(unsigned w) { return __uint_as_float(w << 16); }
; __device__ __forceinline__ float bf_hi(unsigned w) { return __uint_as_float(w & 0xffff0000u); }
; __device__ __forceinline__ bf16 f2bf(float f) { return (bf16)(cvt_pk_nv(f, 0.f) & 0xffffu); }
; __device__ __forceinline__ void gmlp_tile(const Ctx& C, int T, LAS unsigned char* lds, int wave, int lane, int tid) {
;     ...
;         __syncthreads();
;         {
;             float v[32]; float s = 0.f;
; #pragma unroll
;             for (int i = 0; i < 4; ++i) { const v4u w = vraw[i];
;                 v[8 * i + 0] = bf_lo(w.x); v[8 * i + 1] = bf_hi(w.x); v[8 * i + 2] = bf_lo(w.y); v[8 * i + 3] = bf_hi(w.y);
;                 v[8 * i + 4] = bf_lo(w.z); v[8 * i + 5] = bf_hi(w.z); v[8 * i + 6] = bf_lo(w.w); v[8 * i + 7] = bf_hi(w.w); }
;             if (h < 3) {
; #pragma unroll
;                 for (int i = 0; i < 4; ++i) vraw[i] = *(const v4u*)(vsrc + (h + 1) * 128 + 8 * i);
;             }
; #pragma unroll
;             for (int i = 0; i < 32; ++i) s += v[i] * v[i];
;             s += __shfl_xor(s, 1); s += __shfl_xor(s, 2);
;             const float r = rsqrtf(s * (1.f / 128.f) + EPS);
; #pragma unroll
;             for (int i = 0; i < 32; ++i) { v[i] = v[i] * r * gvv[i >> 2][i & 3]; VT[(q * 32 + i) * VT_STRIDE + row] = f2bf(v[i]); }
	s_mov_b64 s[0:1], s[80:81]
	v_add_f32_e32 v32, v32, v33
	ds_bpermute_b32 v33, v184, v32
	s_waitcnt lgkmcnt(0)
	v_add_f32_e32 v32, v32, v33
	v_fmamk_f32 v32, v32, 0x3c000000, v177
	v_mul_f32_e32 v33, 0x4b800000, v32
	v_cmp_gt_f32_e32 vcc, s38, v32
	s_nop 1
	v_cndmask_b32_e32 v32, v32, v33, vcc
	v_rsq_f32_e32 v113, v32
	global_load_dwordx4 v[32:35], v[108:109], off offset:560
	global_load_dwordx4 v[40:43], v[108:109], off offset:544
	global_load_dwordx4 v[52:55], v[108:109], off offset:528
	global_load_dwordx4 v[60:63], v[108:109], off offset:512
	v_mul_f32_e32 v205, 0x45800000, v113
	v_cndmask_b32_e32 v113, v113, v205, vcc
	v_mul_f32_e32 v158, v113, v158
	v_mul_f32_e32 v4, v113, v4
	v_mul_f32_e32 v5, v113, v5
	s_waitcnt vmcnt(8)
	ds_write_b128 v254, v[238:241]
	ds_write_b128 v254, v[242:245] offset:1152
	ds_write_b128 v254, v[246:249] offset:2304
	ds_write_b128 v254, v[250:253] offset:3456
	s_waitcnt lgkmcnt(0)
	ds_read_b64 v[126:127], v255
	ds_read_b64 v[124:125], v255 offset:16
	ds_read_b64 v[122:123], v255 offset:32
	ds_read_b64 v[118:119], v255 offset:48
	ds_read_b64 v[116:117], v255 offset:64
	ds_read_b64 v[120:121], v255 offset:80
	ds_read_b64 v[114:115], v255 offset:96
	ds_read_b64 v[110:111], v255 offset:112
	s_waitcnt lgkmcnt(0)
	v_mul_f32_e32 v140, v140, v158
	v_cvt_pk_bf16_f32 v140, v140, v83
	ds_write_b16 v174, v140
	v_mul_f32_e32 v140, v113, v164
	v_mul_f32_e32 v140, v141, v140
	v_cvt_pk_bf16_f32 v140, v140, v83
	ds_write_b16 v174, v140 offset:272
	v_mul_f32_e32 v140, v113, v165
	v_mul_f32_e32 v140, v142, v140
	v_cvt_pk_bf16_f32 v140, v140, v83
	ds_write_b16 v174, v140 offset:544
	v_mul_f32_e32 v140, v113, v166
	v_mul_f32_e32 v140, v143, v140
	v_cvt_pk_bf16_f32 v140, v140, v83
	ds_write_b16 v174, v140 offset:816
	v_mul_f32_e32 v140, v113, v167
	v_mul_f32_e32 v28, v28, v140
	v_cvt_pk_bf16_f32 v28, v28, v83
	ds_write_b16 v174, v28 offset:1088
	v_mul_f32_e32 v28, v113, v178
	v_mul_f32_e32 v28, v29, v28
	v_cvt_pk_bf16_f32 v28, v28, v83
	ds_write_b16 v174, v28 offset:1360
	v_mul_f32_e32 v28, v113, v179
	v_mul_f32_e32 v28, v30, v28
	v_cvt_pk_bf16_f32 v28, v28, v83
	ds_write_b16 v174, v28 offset:1632
	v_mul_f32_e32 v28, v113, v180
	v_mul_f32_e32 v28, v31, v28
	v_cvt_pk_bf16_f32 v28, v28, v83
	ds_write_b16 v174, v28 offset:1904
	v_mul_f32_e32 v28, v113, v181
	v_mul_f32_e32 v20, v20, v28
	v_cvt_pk_bf16_f32 v20, v20, v83
	ds_write_b16 v174, v20 offset:2176
	v_mul_f32_e32 v20, v113, v189
	v_mul_f32_e32 v20, v21, v20
	v_cvt_pk_bf16_f32 v20, v20, v83
	ds_write_b16 v174, v20 offset:2448
	v_mul_f32_e32 v20, v113, v190
	v_mul_f32_e32 v20, v22, v20
	v_cvt_pk_bf16_f32 v20, v20, v83
	ds_write_b16 v174, v20 offset:2720
	v_mul_f32_e32 v20, v113, v191
	v_mul_f32_e32 v20, v23, v20
	v_cvt_pk_bf16_f32 v20, v20, v83
	ds_write_b16 v174, v20 offset:2992
	v_mul_f32_e32 v20, v113, v192
	v_mul_f32_e32 v16, v16, v20
	v_cvt_pk_bf16_f32 v16, v16, v83
	ds_write_b16 v174, v16 offset:3264
	v_mul_f32_e32 v16, v113, v193
	v_mul_f32_e32 v16, v17, v16
	v_cvt_pk_bf16_f32 v16, v16, v83
	ds_write_b16 v174, v16 offset:3536
	v_mul_f32_e32 v16, v113, v194
	v_mul_f32_e32 v16, v18, v16
	v_cvt_pk_bf16_f32 v16, v16, v83
	ds_write_b16 v174, v16 offset:3808
	v_mul_f32_e32 v16, v113, v195
	v_mul_f32_e32 v16, v19, v16
	v_cvt_pk_bf16_f32 v16, v16, v83
	ds_write_b16 v174, v16 offset:4080
	v_mul_f32_e32 v16, v113, v196
	s_waitcnt vmcnt(4)
	v_mul_f32_e32 v16, v152, v16
	v_cvt_pk_bf16_f32 v16, v16, v83
	ds_write_b16 v174, v16 offset:4352
	v_mul_f32_e32 v16, v113, v197
	v_mul_f32_e32 v16, v153, v16
	v_cvt_pk_bf16_f32 v16, v16, v83
	v_mul_f32_e32 v4, v145, v4
	ds_write_b16 v174, v16 offset:4624
	v_mul_f32_e32 v16, v113, v198
	v_cvt_pk_bf16_f32 v4, v4, v83
	v_mul_f32_e32 v16, v154, v16
	ds_write_b16 v174, v4 offset:6800
	v_mul_f32_e32 v4, v113, v131
	v_cvt_pk_bf16_f32 v16, v16, v83
	v_mul_f32_e32 v4, v146, v4
	ds_write_b16 v174, v16 offset:4896
	v_mul_f32_e32 v16, v113, v199
	v_cvt_pk_bf16_f32 v4, v4, v83
	v_mul_f32_e32 v16, v155, v16
	ds_write_b16 v174, v4 offset:7072
	v_mul_f32_e32 v4, v113, v130
	v_cvt_pk_bf16_f32 v16, v16, v83
	v_mul_f32_e32 v4, v147, v4
	ds_write_b16 v174, v16 offset:5168
	v_mul_f32_e32 v16, v113, v200
	v_cvt_pk_bf16_f32 v4, v4, v83
	v_mul_f32_e32 v16, v148, v16
	ds_write_b16 v174, v4 offset:7344
	v_mul_f32_e32 v4, v113, v161
	v_cvt_pk_bf16_f32 v16, v16, v83
	v_mul_f32_e32 v4, v24, v4
	ds_write_b16 v174, v16 offset:5440
	v_mul_f32_e32 v16, v113, v201
	v_cvt_pk_bf16_f32 v4, v4, v83
	v_mul_f32_e32 v16, v149, v16
	ds_write_b16 v174, v4 offset:7616
	v_mul_f32_e32 v4, v113, v160
	v_cvt_pk_bf16_f32 v16, v16, v83
	v_mul_f32_e32 v4, v25, v4
	ds_write_b16 v174, v16 offset:5712
	v_mul_f32_e32 v16, v113, v202
	v_cvt_pk_bf16_f32 v4, v4, v83
	v_mul_f32_e32 v16, v150, v16
	ds_write_b16 v174, v4 offset:7888
	v_mul_f32_e32 v4, v113, v163
	v_cvt_pk_bf16_f32 v16, v16, v83
	v_mul_f32_e32 v4, v26, v4
	ds_write_b16 v174, v16 offset:5984
	v_mul_f32_e32 v16, v113, v203
	v_cvt_pk_bf16_f32 v4, v4, v83
	v_mul_f32_e32 v16, v151, v16
	ds_write_b16 v174, v4 offset:8160
	v_mul_f32_e32 v4, v113, v162
	v_cvt_pk_bf16_f32 v16, v16, v83
	v_mul_f32_e32 v5, v144, v5
	v_mul_f32_e32 v4, v27, v4
	ds_write_b16 v174, v16 offset:6256
	v_cvt_pk_bf16_f32 v5, v5, v83
	ds_write_b16 v174, v5 offset:6528
	v_cvt_pk_bf16_f32 v4, v4, v83
	ds_write_b16 v174, v4 offset:8432
	s_waitcnt lgkmcnt(0)
	s_barrier
; __device__ __forceinline__ float bf_lo(unsigned w) { return __uint_as_float(w << 16); }
; __device__ __forceinline__ float bf_hi(unsigned w) { return __uint_as_float(w & 0xffff0000u); }
; #define LAS __attribute__((address_space(3)))
; __device__ __forceinline__ unsigned cvt_pk_nv(float lo, float hi) { unsigned r; asm("v_cvt_pk_bf16_f32 %0, %1, %2" : "=v"(r) : "v"(lo), "v"(hi)); return r; }
; __device__ __forceinline__ void gmlp_tile(const Ctx& C, int T, LAS unsigned char* lds, int wave, int lane, int tid) {
;     ...
; #pragma unroll
;         for (int dbi = 0; dbi < 2; ++dbi) {
;             const int db = 2 * dh + dbi;
;             v16f acc;
; #pragma unroll
;             for (int r = 0; r < 16; ++r) acc[r] = 0.f;
; #pragma unroll
;             for (int ks = 0; ks < 8; ++ks) {
;                 const bfx8 va = *(const LAS bfx8*)(VT + (32 * db + tl) * VT_STRIDE + 16 * ks + 8 * hh);
;                 acc = __builtin_amdgcn_mfma_f32_32x32x16_bf16(va, wf[ks], acc, 0, 0, 0);
;             }
; #pragma unroll
;             for (int rg = 0; rg < 4; ++rg) {
;                 const v2u u2 = uw[dbi][rg];
;                 const float o0 = bf_lo(u2.x) * (acc[4 * rg + 0] + bias), o1 = bf_hi(u2.x) * (acc[4 * rg + 1] + bias);
;                 const float o2 = bf_lo(u2.y) * (acc[4 * rg + 2] + bias), o3 = bf_hi(u2.y) * (acc[4 * rg + 3] + bias);
;                 ssq += (o0 * o0 + o1 * o1) + (o2 * o2 + o3 * o3);
;                 outp[h][dbi][2 * rg] = cvt_pk_nv(o0, o1); outp[h][dbi][2 * rg + 1] = cvt_pk_nv(o2, o3);
;             }
	ds_read_b128 v[16:19], v102
	v_add_f32_e32 v4, v128, v7
	v_mul_f32_e32 v113, v4, v6
	v_mul_f32_e32 v4, v112, v112
	v_mul_f32_e32 v5, v113, v113
	v_fmac_f32_e32 v4, v157, v157
	v_fmac_f32_e32 v5, v204, v204
	v_add_f32_e32 v130, v4, v5
	ds_read_b128 v[4:7], v102 offset:32
	s_waitcnt lgkmcnt(1)
	v_mfma_f32_32x32x16_bf16 v[16:31], v[16:19], v[0:3], 0
	ds_read_b128 v[146:149], v102 offset:64
	v_cvt_pk_bf16_f32 v145, v157, v112
	v_lshlrev_b32_e32 v112, 16, v78
	v_cvt_pk_bf16_f32 v142, v204, v113
	v_mul_f32_e32 v112, v8, v112
	v_and_b32_e32 v8, 0xffff0000, v79
	v_add_f32_e32 v129, v130, v129
	s_waitcnt lgkmcnt(1)
	v_mfma_f32_32x32x16_bf16 v[16:31], v[4:7], v[72:75], v[16:31]
	v_and_b32_e32 v4, 0xffff0000, v78
	v_add_f32_e32 v5, v128, v9
	v_mul_f32_e32 v78, v5, v4
	v_lshlrev_b32_e32 v4, 16, v79
	v_add_f32_e32 v5, v128, v10
	v_mul_f32_e32 v113, v5, v4
	ds_read_b128 v[4:7], v102 offset:96
	s_waitcnt lgkmcnt(1)
	v_mfma_f32_32x32x16_bf16 v[16:31], v[146:149], v[68:71], v[16:31]
	v_add_f32_e32 v9, v128, v11
	v_mul_f32_e32 v79, v9, v8
	ds_read_b128 v[8:11], v102 offset:128
	v_mul_f32_e32 v130, v78, v78
	v_mul_f32_e32 v131, v79, v79
	v_fmac_f32_e32 v130, v112, v112
	v_fmac_f32_e32 v131, v113, v113
	s_waitcnt lgkmcnt(1)
	v_mfma_f32_32x32x16_bf16 v[16:31], v[4:7], v[64:67], v[16:31]
	v_add_f32_e32 v4, v130, v131
	v_add_f32_e32 v129, v4, v129
	ds_read_b128 v[4:7], v102 offset:160
	v_cvt_pk_bf16_f32 v146, v112, v78
	v_lshlrev_b32_e32 v78, 16, v76
	v_cvt_pk_bf16_f32 v143, v113, v79
	s_waitcnt vmcnt(0)
	v_and_b32_e32 v189, 0xffff0000, v60
	s_waitcnt lgkmcnt(1)
	v_mfma_f32_32x32x16_bf16 v[16:31], v[8:11], v[56:59], v[16:31]
	v_add_f32_e32 v8, v128, v12
	v_mul_f32_e32 v12, v8, v78
	v_and_b32_e32 v8, 0xffff0000, v76
	v_add_f32_e32 v9, v128, v13
	v_mul_f32_e32 v13, v9, v8
	ds_read_b128 v[8:11], v102 offset:192
	v_lshlrev_b32_e32 v76, 16, v77
	s_waitcnt lgkmcnt(1)
	v_mfma_f32_32x32x16_bf16 v[16:31], v[4:7], v[48:51], v[16:31]
	v_add_f32_e32 v4, v128, v14
	v_mul_f32_e32 v14, v4, v76
	v_and_b32_e32 v4, 0xffff0000, v77
	v_add_f32_e32 v5, v128, v15
	v_mul_f32_e32 v15, v5, v4
	ds_read_b128 v[4:7], v102 offset:224
	v_mul_f32_e32 v76, v13, v13
	s_waitcnt lgkmcnt(1)
	v_mfma_f32_32x32x16_bf16 v[16:31], v[8:11], v[44:47], v[16:31]
	v_mul_f32_e32 v8, v15, v15
	v_fmac_f32_e32 v76, v12, v12
	v_fmac_f32_e32 v8, v14, v14
	v_add_f32_e32 v8, v76, v8
	v_add_f32_e32 v8, v8, v129
	v_cvt_pk_bf16_f32 v147, v12, v13
	v_cvt_pk_bf16_f32 v144, v14, v15
	s_waitcnt lgkmcnt(0)
	v_mfma_f32_32x32x16_bf16 v[16:31], v[4:7], v[36:39], v[16:31]
	v_lshlrev_b32_e32 v4, 16, v126
	v_lshlrev_b32_e32 v162, 16, v60
	v_lshlrev_b32_e32 v198, 16, v61
	v_and_b32_e32 v199, 0xffff0000, v61
	v_lshlrev_b32_e32 v200, 16, v62
	v_and_b32_e32 v201, 0xffff0000, v62
	v_lshlrev_b32_e32 v202, 16, v63
	s_nop 4
	v_add_f32_e32 v5, v159, v16
	v_mul_f32_e32 v4, v5, v4
	v_and_b32_e32 v5, 0xffff0000, v126
	v_add_f32_e32 v6, v159, v17
	v_mul_f32_e32 v5, v6, v5
	v_lshlrev_b32_e32 v6, 16, v127
	v_add_f32_e32 v7, v159, v18
	v_mul_f32_e32 v6, v7, v6
	v_and_b32_e32 v7, 0xffff0000, v127
	v_add_f32_e32 v9, v159, v19
	v_mul_f32_e32 v7, v9, v7
	v_mul_f32_e32 v9, v5, v5
	v_fmac_f32_e32 v9, v4, v4
	v_cvt_pk_bf16_f32 v141, v4, v5
	v_lshlrev_b32_e32 v4, 16, v124
	v_add_f32_e32 v5, v159, v20
	v_mul_f32_e32 v20, v5, v4
	v_and_b32_e32 v4, 0xffff0000, v124
	v_add_f32_e32 v5, v159, v21
	v_mul_f32_e32 v10, v7, v7
	v_mul_f32_e32 v21, v5, v4
	v_lshlrev_b32_e32 v4, 16, v125
	v_add_f32_e32 v5, v159, v22
	v_fmac_f32_e32 v10, v6, v6
	v_cvt_pk_bf16_f32 v140, v6, v7
	v_mul_f32_e32 v22, v5, v4
	ds_read_b128 v[4:7], v102 offset:8704
	ds_read_b128 v[16:19], v102 offset:8736
	v_add_f32_e32 v9, v9, v10
	v_add_f32_e32 v76, v8, v9
	v_and_b32_e32 v8, 0xffff0000, v125
	v_add_f32_e32 v9, v159, v23
	v_mul_f32_e32 v23, v9, v8
	v_mul_f32_e32 v8, v21, v21
	v_mul_f32_e32 v9, v23, v23
	v_fmac_f32_e32 v8, v20, v20
	v_fmac_f32_e32 v9, v22, v22
	v_add_f32_e32 v77, v8, v9
	s_waitcnt lgkmcnt(1)
	v_mfma_f32_32x32x16_bf16 v[0:15], v[4:7], v[0:3], 0
	v_cvt_pk_bf16_f32 v153, v20, v21
	v_lshlrev_b32_e32 v20, 16, v122
	v_add_f32_e32 v21, v159, v24
	v_cvt_pk_bf16_f32 v150, v22, v23
	v_mul_f32_e32 v24, v21, v20
	ds_read_b128 v[20:23], v102 offset:8768
	v_add_f32_e32 v76, v77, v76
	s_waitcnt lgkmcnt(1)
	v_mfma_f32_32x32x16_bf16 v[0:15], v[16:19], v[72:75], v[0:15]
	v_and_b32_e32 v16, 0xffff0000, v122
	v_add_f32_e32 v17, v159, v25
	v_mul_f32_e32 v25, v17, v16
	v_lshlrev_b32_e32 v16, 16, v123
	v_add_f32_e32 v17, v159, v26
	v_mul_f32_e32 v26, v17, v16
	ds_read_b128 v[16:19], v102 offset:8800
	s_waitcnt lgkmcnt(1)
	v_mfma_f32_32x32x16_bf16 v[0:15], v[20:23], v[68:71], v[0:15]
	v_and_b32_e32 v20, 0xffff0000, v123
	v_add_f32_e32 v21, v159, v27
	v_mul_f32_e32 v27, v21, v20
	ds_read_b128 v[20:23], v102 offset:8832
	v_mul_f32_e32 v68, v25, v25
	v_mul_f32_e32 v69, v27, v27
	v_fmac_f32_e32 v68, v24, v24
	s_waitcnt lgkmcnt(1)
	v_mfma_f32_32x32x16_bf16 v[0:15], v[16:19], v[64:67], v[0:15]
	v_fmac_f32_e32 v69, v26, v26
	v_add_f32_e32 v16, v68, v69
	v_add_f32_e32 v64, v16, v76
	ds_read_b128 v[16:19], v102 offset:8864
	v_cvt_pk_bf16_f32 v154, v24, v25
	v_lshlrev_b32_e32 v24, 16, v118
	v_cvt_pk_bf16_f32 v151, v26, v27
	s_waitcnt lgkmcnt(1)
	v_mfma_f32_32x32x16_bf16 v[0:15], v[20:23], v[56:59], v[0:15]
	v_add_f32_e32 v20, v159, v28
	v_mul_f32_e32 v24, v20, v24
	v_and_b32_e32 v20, 0xffff0000, v118
	v_add_f32_e32 v21, v159, v29
	v_mul_f32_e32 v25, v21, v20
	ds_read_b128 v[20:23], v102 offset:8896
	v_lshlrev_b32_e32 v26, 16, v119
	s_waitcnt lgkmcnt(1)
; __device__ __forceinline__ float bf_lo(unsigned w) { return __uint_as_float(w << 16); }
; __device__ __forceinline__ float bf_hi(unsigned w) { return __uint_as_float(w & 0xffff0000u); }
; __device__ __forceinline__ unsigned cvt_pk_nv(float lo, float hi) { unsigned r; asm("v_cvt_pk_bf16_f32 %0, %1, %2" : "=v"(r) : "v"(lo), "v"(hi)); return r; }
;     __device__ __forceinline__ const float* in(int i) const { return karg_in(i); }
; __device__ __forceinline__ void gmlp_tile(const Ctx& C, int T, LAS unsigned char* lds, int wave, int lane, int tid) {
;     ...
;         const bf16* wrow = Weff + ((size_t)(mode * 4 + h) * 128 + t) * 128 + 8 * hh;
; #pragma unroll
;         for (int ks = 0; ks < 8; ++ks) wf[ks] = *(const bfx8*)(wrow + 16 * ks);
;         v2u uw[2][4];
; #pragma unroll
;         for (int dbi = 0; dbi < 2; ++dbi)
; #pragma unroll
;             for (int rg = 0; rg < 4; ++rg) uw[dbi][rg] = *(const v2u*)(zt + h * 128 + 32 * (2 * dh + dbi) + 8 * rg + 4 * hh);
;         const float bias = C.in(13)[h * 128 + (mode ? (t & 15) : t)];
;         v4f gvv[8];
;         { const float* gvp = C.in(11) + h * 128 + q * 32;
; #pragma unroll
;           for (int i = 0; i < 8; ++i) gvv[i] = *(const v4f*)(gvp + 4 * i); }
;     ...
;             for (int rg = 0; rg < 4; ++rg) {
;                 const v2u u2 = uw[dbi][rg];
;                 const float o0 = bf_lo(u2.x) * (acc[4 * rg + 0] + bias), o1 = bf_hi(u2.x) * (acc[4 * rg + 1] + bias);
;                 const float o2 = bf_lo(u2.y) * (acc[4 * rg + 2] + bias), o3 = bf_hi(u2.y) * (acc[4 * rg + 3] + bias);
;                 ssq += (o0 * o0 + o1 * o1) + (o2 * o2 + o3 * o3);
;                 outp[h][dbi][2 * rg] = cvt_pk_nv(o0, o1); outp[h][dbi][2 * rg + 1] = cvt_pk_nv(o2, o3);
;             }
	v_mfma_f32_32x32x16_bf16 v[0:15], v[16:19], v[48:51], v[0:15]
	v_add_f32_e32 v16, v159, v30
	v_mul_f32_e32 v26, v16, v26
	v_and_b32_e32 v16, 0xffff0000, v119
	v_add_f32_e32 v17, v159, v31
	v_mul_f32_e32 v27, v17, v16
	ds_read_b128 v[16:19], v102 offset:8928
	v_mul_f32_e32 v28, v25, v25
	s_waitcnt lgkmcnt(1)
	v_mfma_f32_32x32x16_bf16 v[0:15], v[20:23], v[44:47], v[0:15]
	v_mul_f32_e32 v20, v27, v27
	v_fmac_f32_e32 v28, v24, v24
	v_fmac_f32_e32 v20, v26, v26
	v_add_f32_e32 v20, v28, v20
	v_add_f32_e32 v20, v20, v64
	v_cvt_pk_bf16_f32 v155, v24, v25
	v_cvt_pk_bf16_f32 v152, v26, v27
	s_waitcnt lgkmcnt(0)
	v_mfma_f32_32x32x16_bf16 v[0:15], v[16:19], v[36:39], v[0:15]
	v_lshlrev_b32_e32 v16, 16, v116
	v_mul_f32_e32 v39, v189, v189
	v_fmac_f32_e32 v39, v162, v162
	v_fmac_f32_e32 v39, v198, v198
	v_fmac_f32_e32 v39, v199, v199
	v_fmac_f32_e32 v39, v200, v200
	v_fmac_f32_e32 v39, v201, v201
	s_nop 4
	v_add_f32_e32 v0, v159, v0
	v_mul_f32_e32 v0, v0, v16
	v_and_b32_e32 v16, 0xffff0000, v116
	v_add_f32_e32 v1, v159, v1
	v_mul_f32_e32 v1, v1, v16
	v_lshlrev_b32_e32 v16, 16, v117
	v_add_f32_e32 v2, v159, v2
	v_mul_f32_e32 v2, v2, v16
	v_and_b32_e32 v16, 0xffff0000, v117
	v_add_f32_e32 v3, v159, v3
	v_mul_f32_e32 v3, v3, v16
	v_mul_f32_e32 v16, v1, v1
	v_mul_f32_e32 v17, v3, v3
	v_fmac_f32_e32 v16, v0, v0
	v_fmac_f32_e32 v17, v2, v2
	v_add_f32_e32 v16, v16, v17
	v_add_f32_e32 v157, v20, v16
	v_add_co_u32_e32 v16, vcc, s40, v104
	v_cvt_pk_bf16_f32 v149, v0, v1
	v_cvt_pk_bf16_f32 v148, v2, v3
	v_add_f32_e32 v4, v159, v4
	s_nop 0
	v_addc_co_u32_e32 v17, vcc, 0, v105, vcc
	global_load_dwordx4 v[0:3], v[16:17], off offset:-3584
	global_load_dwordx4 v[76:79], v[16:17], off offset:-2560
	global_load_dwordx4 v[72:75], v[16:17], off offset:-1536
	global_load_dwordx4 v[68:71], v[16:17], off offset:-512
	global_load_dwordx4 v[64:67], v[16:17], off offset:512
	global_load_dwordx4 v[56:59], v[16:17], off offset:1536
	global_load_dwordx4 v[48:51], v[16:17], off offset:2560
	global_load_dwordx4 v[44:47], v[16:17], off offset:3584
	global_load_dwordx4 v[238:241], v[236:237], off offset:512
	v_lshl_add_u64 v[236:237], v[236:237], 0, s[98:99]
	global_load_dwordx4 v[242:245], v[236:237], off offset:512
	v_lshl_add_u64 v[236:237], v[236:237], 0, s[98:99]
	global_load_dwordx4 v[246:249], v[236:237], off offset:512
	v_lshl_add_u64 v[236:237], v[236:237], 0, s[98:99]
	global_load_dwordx4 v[250:253], v[236:237], off offset:512
	v_lshl_add_u64 v[236:237], v[236:237], 0, s[100:101]
	s_load_dwordx2 s[0:1], s[0:1], 0x68
	v_lshlrev_b32_e32 v16, 16, v120
	v_mul_f32_e32 v158, v4, v16
	v_and_b32_e32 v203, 0xffff0000, v63
	v_fmac_f32_e32 v39, v202, v202
	s_waitcnt lgkmcnt(0)
	global_load_dword v163, v156, s[0:1] offset:1024
	s_mov_b64 s[0:1], s[80:81]
	s_load_dwordx2 s[28:29], s[0:1], 0x58
	s_waitcnt lgkmcnt(0)
	global_load_dwordx4 v[16:19], v139, s[28:29] offset:1072
	global_load_dwordx4 v[20:23], v139, s[28:29] offset:1056
	global_load_dwordx4 v[24:27], v139, s[28:29] offset:1040
	global_load_dwordx4 v[28:31], v139, s[28:29] offset:1024
	v_lshlrev_b32_e32 v204, 16, v52
	v_fmac_f32_e32 v39, v203, v203
	v_and_b32_e32 v205, 0xffff0000, v52
	v_fmac_f32_e32 v39, v204, v204
	v_lshlrev_b32_e32 v206, 16, v53
	v_fmac_f32_e32 v39, v205, v205
	v_and_b32_e32 v207, 0xffff0000, v53
	v_fmac_f32_e32 v39, v206, v206
	v_lshlrev_b32_e32 v208, 16, v54
	v_fmac_f32_e32 v39, v207, v207
	v_and_b32_e32 v209, 0xffff0000, v54
	v_fmac_f32_e32 v39, v208, v208
	v_lshlrev_b32_e32 v210, 16, v55
	v_fmac_f32_e32 v39, v209, v209
	v_and_b32_e32 v211, 0xffff0000, v55
	v_fmac_f32_e32 v39, v210, v210
	v_lshlrev_b32_e32 v212, 16, v40
	v_fmac_f32_e32 v39, v211, v211
	v_and_b32_e32 v213, 0xffff0000, v40
	v_fmac_f32_e32 v39, v212, v212
	v_lshlrev_b32_e32 v214, 16, v41
	v_fmac_f32_e32 v39, v213, v213
	v_and_b32_e32 v215, 0xffff0000, v41
	v_fmac_f32_e32 v39, v214, v214
	v_lshlrev_b32_e32 v216, 16, v42
	v_fmac_f32_e32 v39, v215, v215
	v_and_b32_e32 v217, 0xffff0000, v42
	v_fmac_f32_e32 v39, v216, v216
	v_and_b32_e32 v4, 0xffff0000, v120
	v_add_f32_e32 v5, v159, v5
	v_lshlrev_b32_e32 v218, 16, v43
	v_fmac_f32_e32 v39, v217, v217
	v_mul_f32_e32 v120, v5, v4
	v_and_b32_e32 v219, 0xffff0000, v43
	v_fmac_f32_e32 v39, v218, v218
	v_and_b32_e32 v4, 0xffff0000, v32
	v_lshlrev_b32_e32 v5, 16, v32
	global_load_dwordx4 v[40:43], v139, s[28:29] offset:1136
	global_load_dwordx4 v[164:167], v139, s[28:29] offset:1120
	global_load_dwordx4 v[178:181], v139, s[28:29] offset:1104
	global_load_dwordx4 v[190:193], v139, s[28:29] offset:1088
	v_fmac_f32_e32 v39, v219, v219
	v_pk_mul_f32 v[36:37], v[4:5], v[4:5]
	v_and_b32_e32 v160, 0xffff0000, v33
	v_add_f32_e32 v32, v37, v39
	v_lshlrev_b32_e32 v161, 16, v33
	v_add_f32_e32 v36, v36, v32
	v_pk_mul_f32 v[32:33], v[160:161], v[160:161]
	v_and_b32_e32 v194, 0xffff0000, v34
	v_add_f32_e32 v33, v33, v36
	v_lshlrev_b32_e32 v195, 16, v34
	v_add_f32_e32 v36, v32, v33
	v_pk_mul_f32 v[32:33], v[194:195], v[194:195]
	v_and_b32_e32 v196, 0xffff0000, v35
	v_add_f32_e32 v33, v33, v36
	v_lshlrev_b32_e32 v197, 16, v35
	v_add_f32_e32 v34, v32, v33
	v_pk_mul_f32 v[32:33], v[196:197], v[196:197]
	v_lshlrev_b32_e32 v38, 16, v121
	v_add_f32_e32 v33, v33, v34
	v_add_f32_e32 v32, v32, v33
	ds_bpermute_b32 v33, v183, v32
	v_add_f32_e32 v6, v159, v6
	v_mul_f32_e32 v220, v6, v38
	v_and_b32_e32 v6, 0xffff0000, v121
	s_waitcnt lgkmcnt(0)
	v_add_f32_e32 v32, v32, v33
	ds_bpermute_b32 v33, v184, v32
	s_barrier
; __device__ __forceinline__ float bf_lo(unsigned w) { return __uint_as_float(w << 16); }
; __device__ __forceinline__ float bf_hi(unsigned w) { return __uint_as_float(w & 0xffff0000u); }
; __device__ __forceinline__ bf16 f2bf(float f) { return (bf16)(cvt_pk_nv(f, 0.f) & 0xffffu); }
; __device__ __forceinline__ void gmlp_tile(const Ctx& C, int T, LAS unsigned char* lds, int wave, int lane, int tid) {
;     ...
;         __syncthreads();
;         {
;             float v[32]; float s = 0.f;
; #pragma unroll
;             for (int i = 0; i < 4; ++i) { const v4u w = vraw[i];
;                 v[8 * i + 0] = bf_lo(w.x); v[8 * i + 1] = bf_hi(w.x); v[8 * i + 2] = bf_lo(w.y); v[8 * i + 3] = bf_hi(w.y);
;                 v[8 * i + 4] = bf_lo(w.z); v[8 * i + 5] = bf_hi(w.z); v[8 * i + 6] = bf_lo(w.w); v[8 * i + 7] = bf_hi(w.w); }
;             if (h < 3) {
; #pragma unroll
;                 for (int i = 0; i < 4; ++i) vraw[i] = *(const v4u*)(vsrc + (h + 1) * 128 + 8 * i);
;             }
; #pragma unroll
;             for (int i = 0; i < 32; ++i) s += v[i] * v[i];
;             s += __shfl_xor(s, 1); s += __shfl_xor(s, 2);
;             const float r = rsqrtf(s * (1.f / 128.f) + EPS);
; #pragma unroll
;             for (int i = 0; i < 32; ++i) { v[i] = v[i] * r * gvv[i >> 2][i & 3]; VT[(q * 32 + i) * VT_STRIDE + row] = f2bf(v[i]); }
	s_waitcnt lgkmcnt(0)
	v_add_f32_e32 v8, v159, v8
	s_mov_b64 s[0:1], s[80:81]
	v_add_f32_e32 v32, v32, v33
	v_fmamk_f32 v32, v32, 0x3c000000, v177
	v_mul_f32_e32 v33, 0x4b800000, v32
	v_cmp_gt_f32_e32 vcc, s38, v32
	s_nop 1
	v_cndmask_b32_e32 v32, v32, v33, vcc
	v_rsq_f32_e32 v121, v32
	global_load_dwordx4 v[36:39], v[108:109], off offset:768
	global_load_dwordx4 v[52:55], v[108:109], off offset:784
	global_load_dwordx4 v[32:35], v[108:109], off offset:816
	global_load_dwordx4 v[60:63], v[108:109], off offset:800
	v_mul_f32_e32 v108, 0x45800000, v121
	v_cndmask_b32_e32 v108, v121, v108, vcc
	v_mul_f32_e32 v109, v108, v162
	s_waitcnt vmcnt(8)
	ds_write_b128 v254, v[238:241]
	ds_write_b128 v254, v[242:245] offset:1152
	ds_write_b128 v254, v[246:249] offset:2304
	ds_write_b128 v254, v[250:253] offset:3456
	s_waitcnt lgkmcnt(0)
	ds_read_b64 v[130:131], v255
	ds_read_b64 v[128:129], v255 offset:16
	ds_read_b64 v[126:127], v255 offset:32
	ds_read_b64 v[124:125], v255 offset:48
	ds_read_b64 v[122:123], v255 offset:64
	ds_read_b64 v[118:119], v255 offset:80
	ds_read_b64 v[116:117], v255 offset:96
	ds_read_b64 v[112:113], v255 offset:112
	s_waitcnt lgkmcnt(0)
	v_mul_f32_e32 v28, v28, v109
	v_cvt_pk_bf16_f32 v28, v28, v83
	ds_write_b16 v174, v28
	v_mul_f32_e32 v28, v108, v189
	v_mul_f32_e32 v28, v29, v28
	v_cvt_pk_bf16_f32 v28, v28, v83
	ds_write_b16 v174, v28 offset:272
	v_mul_f32_e32 v28, v108, v198
	v_mul_f32_e32 v28, v30, v28
	v_cvt_pk_bf16_f32 v28, v28, v83
	ds_write_b16 v174, v28 offset:544
	v_mul_f32_e32 v28, v108, v199
	v_mul_f32_e32 v28, v31, v28
	v_cvt_pk_bf16_f32 v28, v28, v83
	ds_write_b16 v174, v28 offset:816
	v_mul_f32_e32 v28, v108, v200
	v_mul_f32_e32 v24, v24, v28
	v_cvt_pk_bf16_f32 v24, v24, v83
	ds_write_b16 v174, v24 offset:1088
	v_mul_f32_e32 v24, v108, v201
	v_mul_f32_e32 v24, v25, v24
	v_cvt_pk_bf16_f32 v24, v24, v83
	ds_write_b16 v174, v24 offset:1360
	v_mul_f32_e32 v24, v108, v202
	v_mul_f32_e32 v24, v26, v24
	v_cvt_pk_bf16_f32 v24, v24, v83
	ds_write_b16 v174, v24 offset:1632
	v_mul_f32_e32 v24, v108, v203
	v_mul_f32_e32 v24, v27, v24
	v_cvt_pk_bf16_f32 v24, v24, v83
	ds_write_b16 v174, v24 offset:1904
	v_mul_f32_e32 v24, v108, v204
	v_mul_f32_e32 v20, v20, v24
	v_cvt_pk_bf16_f32 v20, v20, v83
	ds_write_b16 v174, v20 offset:2176
	v_mul_f32_e32 v20, v108, v205
	v_mul_f32_e32 v20, v21, v20
	v_cvt_pk_bf16_f32 v20, v20, v83
	ds_write_b16 v174, v20 offset:2448
	v_mul_f32_e32 v20, v108, v206
	v_mul_f32_e32 v20, v22, v20
	v_cvt_pk_bf16_f32 v20, v20, v83
	ds_write_b16 v174, v20 offset:2720
	v_mul_f32_e32 v20, v108, v207
	v_mul_f32_e32 v20, v23, v20
	v_cvt_pk_bf16_f32 v20, v20, v83
	ds_write_b16 v174, v20 offset:2992
	v_mul_f32_e32 v20, v108, v208
	v_mul_f32_e32 v16, v16, v20
	v_cvt_pk_bf16_f32 v16, v16, v83
	ds_write_b16 v174, v16 offset:3264
	v_mul_f32_e32 v16, v108, v209
	v_mul_f32_e32 v16, v17, v16
	v_cvt_pk_bf16_f32 v16, v16, v83
	ds_write_b16 v174, v16 offset:3536
	v_mul_f32_e32 v16, v108, v210
	v_mul_f32_e32 v16, v18, v16
	v_cvt_pk_bf16_f32 v16, v16, v83
	ds_write_b16 v174, v16 offset:3808
	v_mul_f32_e32 v16, v108, v211
	v_mul_f32_e32 v16, v19, v16
	v_cvt_pk_bf16_f32 v16, v16, v83
	ds_write_b16 v174, v16 offset:4080
	v_mul_f32_e32 v16, v108, v212
	s_waitcnt vmcnt(4)
	v_mul_f32_e32 v16, v190, v16
	v_cvt_pk_bf16_f32 v16, v16, v83
	ds_write_b16 v174, v16 offset:4352
	v_mul_f32_e32 v16, v108, v213
	v_mul_f32_e32 v16, v191, v16
	v_mul_f32_e32 v4, v108, v4
	v_cvt_pk_bf16_f32 v16, v16, v83
	v_mul_f32_e32 v4, v165, v4
	ds_write_b16 v174, v16 offset:4624
	v_mul_f32_e32 v16, v108, v214
	v_cvt_pk_bf16_f32 v4, v4, v83
	v_mul_f32_e32 v16, v192, v16
	ds_write_b16 v174, v4 offset:6800
	v_mul_f32_e32 v4, v108, v161
	v_cvt_pk_bf16_f32 v16, v16, v83
	v_mul_f32_e32 v4, v166, v4
	ds_write_b16 v174, v16 offset:4896
	v_mul_f32_e32 v16, v108, v215
	v_cvt_pk_bf16_f32 v4, v4, v83
	v_mul_f32_e32 v16, v193, v16
	ds_write_b16 v174, v4 offset:7072
	v_mul_f32_e32 v4, v108, v160
	v_cvt_pk_bf16_f32 v16, v16, v83
	v_mul_f32_e32 v4, v167, v4
	ds_write_b16 v174, v16 offset:5168
	v_mul_f32_e32 v16, v108, v216
	v_cvt_pk_bf16_f32 v4, v4, v83
	v_mul_f32_e32 v16, v178, v16
	ds_write_b16 v174, v4 offset:7344
	v_mul_f32_e32 v4, v108, v195
	v_cvt_pk_bf16_f32 v16, v16, v83
	v_mul_f32_e32 v4, v40, v4
	ds_write_b16 v174, v16 offset:5440
	v_mul_f32_e32 v16, v108, v217
	v_cvt_pk_bf16_f32 v4, v4, v83
	v_mul_f32_e32 v16, v179, v16
	ds_write_b16 v174, v4 offset:7616
	v_mul_f32_e32 v4, v108, v194
	v_cvt_pk_bf16_f32 v16, v16, v83
	v_mul_f32_e32 v4, v41, v4
	ds_write_b16 v174, v16 offset:5712
	v_mul_f32_e32 v16, v108, v218
	v_cvt_pk_bf16_f32 v4, v4, v83
	v_mul_f32_e32 v16, v180, v16
	ds_write_b16 v174, v4 offset:7888
	v_mul_f32_e32 v4, v108, v197
	v_cvt_pk_bf16_f32 v16, v16, v83
	v_mul_f32_e32 v4, v42, v4
	ds_write_b16 v174, v16 offset:5984
	v_mul_f32_e32 v16, v108, v219
	v_cvt_pk_bf16_f32 v4, v4, v83
	v_mul_f32_e32 v16, v181, v16
	v_mul_f32_e32 v5, v108, v5
	ds_write_b16 v174, v4 offset:8160
	v_mul_f32_e32 v4, v108, v196
	v_cvt_pk_bf16_f32 v16, v16, v83
	v_mul_f32_e32 v5, v164, v5
	v_mul_f32_e32 v4, v43, v4
	ds_write_b16 v174, v16 offset:6256
	v_cvt_pk_bf16_f32 v5, v5, v83
	ds_write_b16 v174, v5 offset:6528
	v_cvt_pk_bf16_f32 v4, v4, v83
	ds_write_b16 v174, v4 offset:8432
	s_waitcnt lgkmcnt(0)
	s_barrier
; __device__ __forceinline__ float bf_lo(unsigned w) { return __uint_as_float(w << 16); }
; __device__ __forceinline__ float bf_hi(unsigned w) { return __uint_as_float(w & 0xffff0000u); }
; #define LAS __attribute__((address_space(3)))
; __device__ __forceinline__ unsigned cvt_pk_nv(float lo, float hi) { unsigned r; asm("v_cvt_pk_bf16_f32 %0, %1, %2" : "=v"(r) : "v"(lo), "v"(hi)); return r; }
; __device__ __forceinline__ void gmlp_tile(const Ctx& C, int T, LAS unsigned char* lds, int wave, int lane, int tid) {
;     ...
; #pragma unroll
;         for (int dbi = 0; dbi < 2; ++dbi) {
;             const int db = 2 * dh + dbi;
;             v16f acc;
; #pragma unroll
;             for (int r = 0; r < 16; ++r) acc[r] = 0.f;
; #pragma unroll
;             for (int ks = 0; ks < 8; ++ks) {
;                 const bfx8 va = *(const LAS bfx8*)(VT + (32 * db + tl) * VT_STRIDE + 16 * ks + 8 * hh);
;                 acc = __builtin_amdgcn_mfma_f32_32x32x16_bf16(va, wf[ks], acc, 0, 0, 0);
;             }
; #pragma unroll
;             for (int rg = 0; rg < 4; ++rg) {
;                 const v2u u2 = uw[dbi][rg];
;                 const float o0 = bf_lo(u2.x) * (acc[4 * rg + 0] + bias), o1 = bf_hi(u2.x) * (acc[4 * rg + 1] + bias);
;                 const float o2 = bf_lo(u2.y) * (acc[4 * rg + 2] + bias), o3 = bf_hi(u2.y) * (acc[4 * rg + 3] + bias);
;                 ssq += (o0 * o0 + o1 * o1) + (o2 * o2 + o3 * o3);
;                 outp[h][dbi][2 * rg] = cvt_pk_nv(o0, o1); outp[h][dbi][2 * rg + 1] = cvt_pk_nv(o2, o3);
;             }
	ds_read_b128 v[16:19], v102
	v_add_f32_e32 v4, v159, v7
	v_mul_f32_e32 v40, v4, v6
	v_mul_f32_e32 v4, v120, v120
	v_mul_f32_e32 v5, v40, v40
	v_fmac_f32_e32 v4, v158, v158
	v_fmac_f32_e32 v5, v220, v220
	v_add_f32_e32 v41, v4, v5
	ds_read_b128 v[4:7], v102 offset:32
	s_waitcnt lgkmcnt(1)
	v_mfma_f32_32x32x16_bf16 v[16:31], v[16:19], v[0:3], 0
	v_add_f32_e32 v108, v41, v157
	v_cvt_pk_bf16_f32 v157, v220, v40
	v_lshlrev_b32_e32 v40, 16, v114
	v_mul_f32_e32 v109, v8, v40
	ds_read_b128 v[40:43], v102 offset:64
	v_cvt_pk_bf16_f32 v160, v158, v120
	v_and_b32_e32 v8, 0xffff0000, v115
	s_waitcnt lgkmcnt(1)
	v_mfma_f32_32x32x16_bf16 v[16:31], v[4:7], v[76:79], v[16:31]
	v_and_b32_e32 v4, 0xffff0000, v114
	v_add_f32_e32 v5, v159, v9
	v_mul_f32_e32 v114, v5, v4
	v_lshlrev_b32_e32 v4, 16, v115
	v_add_f32_e32 v5, v159, v10
	v_mul_f32_e32 v120, v5, v4
	ds_read_b128 v[4:7], v102 offset:96
	s_waitcnt lgkmcnt(1)
	v_mfma_f32_32x32x16_bf16 v[16:31], v[40:43], v[72:75], v[16:31]
	v_add_f32_e32 v9, v159, v11
	v_mul_f32_e32 v40, v9, v8
	ds_read_b128 v[8:11], v102 offset:128
	v_mul_f32_e32 v41, v114, v114
	v_mul_f32_e32 v42, v40, v40
	v_fmac_f32_e32 v41, v109, v109
	v_fmac_f32_e32 v42, v120, v120
	s_waitcnt lgkmcnt(1)
	v_mfma_f32_32x32x16_bf16 v[16:31], v[4:7], v[68:71], v[16:31]
	v_add_f32_e32 v4, v41, v42
	v_add_f32_e32 v41, v4, v108
	ds_read_b128 v[4:7], v102 offset:160
	v_cvt_pk_bf16_f32 v158, v120, v40
	v_lshlrev_b32_e32 v40, 16, v110
	v_cvt_pk_bf16_f32 v161, v109, v114
	s_waitcnt vmcnt(3)
	v_and_b32_e32 v212, 0xffff0000, v36
	s_waitcnt lgkmcnt(1)
	v_mfma_f32_32x32x16_bf16 v[16:31], v[8:11], v[64:67], v[16:31]
	v_add_f32_e32 v8, v159, v12
	v_mul_f32_e32 v12, v8, v40
	v_and_b32_e32 v8, 0xffff0000, v110
	v_add_f32_e32 v9, v159, v13
	v_mul_f32_e32 v13, v9, v8
	ds_read_b128 v[8:11], v102 offset:192
	v_lshlrev_b32_e32 v40, 16, v111
	s_waitcnt lgkmcnt(1)
	v_mfma_f32_32x32x16_bf16 v[16:31], v[4:7], v[56:59], v[16:31]
	v_add_f32_e32 v4, v159, v14
	v_mul_f32_e32 v14, v4, v40
	v_and_b32_e32 v4, 0xffff0000, v111
	v_add_f32_e32 v5, v159, v15
	v_mul_f32_e32 v15, v5, v4
	ds_read_b128 v[4:7], v102 offset:224
	v_mul_f32_e32 v40, v13, v13
	s_waitcnt lgkmcnt(1)
	v_mfma_f32_32x32x16_bf16 v[16:31], v[8:11], v[48:51], v[16:31]
	v_mul_f32_e32 v8, v15, v15
	v_fmac_f32_e32 v40, v12, v12
	v_fmac_f32_e32 v8, v14, v14
	v_add_f32_e32 v8, v40, v8
	v_add_f32_e32 v8, v8, v41
	v_cvt_pk_bf16_f32 v162, v12, v13
	v_cvt_pk_bf16_f32 v159, v14, v15
	s_waitcnt lgkmcnt(0)
	v_mfma_f32_32x32x16_bf16 v[16:31], v[4:7], v[44:47], v[16:31]
	v_lshlrev_b32_e32 v4, 16, v130
	v_and_b32_e32 v208, 0xffff0000, v38
	v_lshlrev_b32_e32 v209, 16, v38
	v_lshlrev_b32_e32 v213, 16, v36
	v_mul_f32_e32 v38, v212, v212
	v_lshlrev_b32_e32 v211, 16, v37
	v_fmac_f32_e32 v38, v213, v213
	s_nop 4
	v_add_f32_e32 v5, v163, v16
	v_mul_f32_e32 v4, v5, v4
	v_and_b32_e32 v5, 0xffff0000, v130
	v_add_f32_e32 v6, v163, v17
	v_mul_f32_e32 v5, v6, v5
	v_lshlrev_b32_e32 v6, 16, v131
	v_add_f32_e32 v7, v163, v18
	v_mul_f32_e32 v6, v7, v6
	v_and_b32_e32 v7, 0xffff0000, v131
	v_add_f32_e32 v9, v163, v19
	v_mul_f32_e32 v7, v9, v7
	v_mul_f32_e32 v9, v5, v5
	v_fmac_f32_e32 v9, v4, v4
	v_cvt_pk_bf16_f32 v131, v4, v5
	v_lshlrev_b32_e32 v4, 16, v128
	v_add_f32_e32 v5, v163, v20
	v_mul_f32_e32 v20, v5, v4
	v_and_b32_e32 v4, 0xffff0000, v128
	v_add_f32_e32 v5, v163, v21
	v_mul_f32_e32 v10, v7, v7
	v_mul_f32_e32 v21, v5, v4
	v_lshlrev_b32_e32 v4, 16, v129
	v_add_f32_e32 v5, v163, v22
	v_fmac_f32_e32 v10, v6, v6
	v_cvt_pk_bf16_f32 v130, v6, v7
	v_mul_f32_e32 v22, v5, v4
	ds_read_b128 v[4:7], v102 offset:8704
	ds_read_b128 v[16:19], v102 offset:8736
	v_add_f32_e32 v9, v9, v10
	v_add_f32_e32 v40, v8, v9
	v_and_b32_e32 v8, 0xffff0000, v129
	v_add_f32_e32 v9, v163, v23
	v_mul_f32_e32 v23, v9, v8
	v_mul_f32_e32 v8, v21, v21
	v_mul_f32_e32 v9, v23, v23
	v_fmac_f32_e32 v8, v20, v20
	v_fmac_f32_e32 v9, v22, v22
	v_add_f32_e32 v41, v8, v9
	s_waitcnt lgkmcnt(1)
	v_mfma_f32_32x32x16_bf16 v[0:15], v[4:7], v[0:3], 0
	v_cvt_pk_bf16_f32 v129, v20, v21
	v_lshlrev_b32_e32 v20, 16, v126
	v_add_f32_e32 v21, v163, v24
	v_cvt_pk_bf16_f32 v128, v22, v23
	v_mul_f32_e32 v24, v21, v20
	ds_read_b128 v[20:23], v102 offset:8768
	v_add_f32_e32 v40, v41, v40
	s_waitcnt lgkmcnt(1)
	v_mfma_f32_32x32x16_bf16 v[0:15], v[16:19], v[76:79], v[0:15]
	v_and_b32_e32 v16, 0xffff0000, v126
	v_add_f32_e32 v17, v163, v25
	v_mul_f32_e32 v25, v17, v16
	v_lshlrev_b32_e32 v16, 16, v127
	v_add_f32_e32 v17, v163, v26
	v_mul_f32_e32 v26, v17, v16
	ds_read_b128 v[16:19], v102 offset:8800
	s_waitcnt lgkmcnt(1)
	v_mfma_f32_32x32x16_bf16 v[0:15], v[20:23], v[72:75], v[0:15]
	v_and_b32_e32 v20, 0xffff0000, v127
	v_add_f32_e32 v21, v163, v27
	v_mul_f32_e32 v27, v21, v20
	ds_read_b128 v[20:23], v102 offset:8832
	v_mul_f32_e32 v41, v25, v25
	v_mul_f32_e32 v42, v27, v27
	v_fmac_f32_e32 v41, v24, v24
	s_waitcnt lgkmcnt(1)
	v_mfma_f32_32x32x16_bf16 v[0:15], v[16:19], v[68:71], v[0:15]
	v_fmac_f32_e32 v42, v26, v26
	v_add_f32_e32 v16, v41, v42
	v_add_f32_e32 v40, v16, v40
	ds_read_b128 v[16:19], v102 offset:8864
	v_cvt_pk_bf16_f32 v127, v24, v25
	v_lshlrev_b32_e32 v24, 16, v124
	v_cvt_pk_bf16_f32 v126, v26, v27
	s_waitcnt lgkmcnt(1)
	v_mfma_f32_32x32x16_bf16 v[0:15], v[20:23], v[64:67], v[0:15]
	v_add_f32_e32 v20, v163, v28
	v_mul_f32_e32 v24, v20, v24
	v_and_b32_e32 v20, 0xffff0000, v124
	v_add_f32_e32 v21, v163, v29
	v_mul_f32_e32 v25, v21, v20
	ds_read_b128 v[20:23], v102 offset:8896
	v_lshlrev_b32_e32 v26, 16, v125
	s_waitcnt lgkmcnt(1)
	v_mfma_f32_32x32x16_bf16 v[0:15], v[16:19], v[56:59], v[0:15]
	v_add_f32_e32 v16, v163, v30
	v_mul_f32_e32 v26, v16, v26
	v_and_b32_e32 v16, 0xffff0000, v125
	v_add_f32_e32 v17, v163, v31
	v_mul_f32_e32 v27, v17, v16
	ds_read_b128 v[16:19], v102 offset:8928
	v_mul_f32_e32 v28, v25, v25
	s_waitcnt lgkmcnt(1)
; __device__ __forceinline__ float bf_lo(unsigned w) { return __uint_as_float(w << 16); }
; __device__ __forceinline__ float bf_hi(unsigned w) { return __uint_as_float(w & 0xffff0000u); }
; __device__ __forceinline__ unsigned cvt_pk_nv(float lo, float hi) { unsigned r; asm("v_cvt_pk_bf16_f32 %0, %1, %2" : "=v"(r) : "v"(lo), "v"(hi)); return r; }
;     __device__ __forceinline__ const float* in(int i) const { return karg_in(i); }
; __device__ __forceinline__ void gmlp_tile(const Ctx& C, int T, LAS unsigned char* lds, int wave, int lane, int tid) {
;     ...
;         const bf16* wrow = Weff + ((size_t)(mode * 4 + h) * 128 + t) * 128 + 8 * hh;
; #pragma unroll
;         for (int ks = 0; ks < 8; ++ks) wf[ks] = *(const bfx8*)(wrow + 16 * ks);
;         v2u uw[2][4];
; #pragma unroll
;         for (int dbi = 0; dbi < 2; ++dbi)
; #pragma unroll
;             for (int rg = 0; rg < 4; ++rg) uw[dbi][rg] = *(const v2u*)(zt + h * 128 + 32 * (2 * dh + dbi) + 8 * rg + 4 * hh);
;         const float bias = C.in(13)[h * 128 + (mode ? (t & 15) : t)];
;         v4f gvv[8];
;         { const float* gvp = C.in(11) + h * 128 + q * 32;
; #pragma unroll
;           for (int i = 0; i < 8; ++i) gvv[i] = *(const v4f*)(gvp + 4 * i); }
;     ...
;             for (int rg = 0; rg < 4; ++rg) {
;                 const v2u u2 = uw[dbi][rg];
;                 const float o0 = bf_lo(u2.x) * (acc[4 * rg + 0] + bias), o1 = bf_hi(u2.x) * (acc[4 * rg + 1] + bias);
;                 const float o2 = bf_lo(u2.y) * (acc[4 * rg + 2] + bias), o3 = bf_hi(u2.y) * (acc[4 * rg + 3] + bias);
;                 ssq += (o0 * o0 + o1 * o1) + (o2 * o2 + o3 * o3);
;                 outp[h][dbi][2 * rg] = cvt_pk_nv(o0, o1); outp[h][dbi][2 * rg + 1] = cvt_pk_nv(o2, o3);
;             }
	v_mfma_f32_32x32x16_bf16 v[0:15], v[20:23], v[48:51], v[0:15]
	v_mul_f32_e32 v20, v27, v27
	v_fmac_f32_e32 v28, v24, v24
	v_fmac_f32_e32 v20, v26, v26
	v_add_f32_e32 v20, v28, v20
	v_add_f32_e32 v20, v20, v40
	v_cvt_pk_bf16_f32 v125, v24, v25
	v_cvt_pk_bf16_f32 v124, v26, v27
	s_waitcnt lgkmcnt(0)
	v_mfma_f32_32x32x16_bf16 v[0:15], v[16:19], v[44:47], v[0:15]
	v_lshlrev_b32_e32 v16, 16, v122
	v_and_b32_e32 v210, 0xffff0000, v37
	v_fmac_f32_e32 v38, v211, v211
	v_fmac_f32_e32 v38, v210, v210
	v_fmac_f32_e32 v38, v209, v209
	v_lshlrev_b32_e32 v207, 16, v39
	v_fmac_f32_e32 v38, v208, v208
	s_nop 4
	v_add_f32_e32 v0, v163, v0
	v_mul_f32_e32 v18, v0, v16
	v_and_b32_e32 v0, 0xffff0000, v122
	v_add_f32_e32 v1, v163, v1
	v_mul_f32_e32 v19, v1, v0
	v_lshlrev_b32_e32 v0, 16, v123
	v_add_f32_e32 v1, v163, v2
	v_mul_f32_e32 v21, v1, v0
	v_and_b32_e32 v0, 0xffff0000, v123
	v_add_f32_e32 v1, v163, v3
	v_mul_f32_e32 v22, v1, v0
	v_mul_f32_e32 v0, v19, v19
	v_mul_f32_e32 v1, v22, v22
	v_add_co_u32_e32 v16, vcc, s41, v104
	v_fmac_f32_e32 v0, v18, v18
	v_fmac_f32_e32 v1, v21, v21
	v_addc_co_u32_e32 v17, vcc, 0, v105, vcc
	v_add_f32_e32 v23, v0, v1
	global_load_dwordx4 v[0:3], v[16:17], off offset:-3584
	global_load_dwordx4 v[72:75], v[16:17], off offset:-2560
	global_load_dwordx4 v[68:71], v[16:17], off offset:-1536
	global_load_dwordx4 v[64:67], v[16:17], off offset:-512
	global_load_dwordx4 v[56:59], v[16:17], off offset:512
	global_load_dwordx4 v[48:51], v[16:17], off offset:1536
	global_load_dwordx4 v[44:47], v[16:17], off offset:2560
	global_load_dwordx4 v[40:43], v[16:17], off offset:3584
	global_load_dwordx4 v[238:241], v[236:237], off offset:768
	v_lshl_add_u64 v[236:237], v[236:237], 0, s[98:99]
	global_load_dwordx4 v[242:245], v[236:237], off offset:768
	v_lshl_add_u64 v[236:237], v[236:237], 0, s[98:99]
	global_load_dwordx4 v[246:249], v[236:237], off offset:768
	v_lshl_add_u64 v[236:237], v[236:237], 0, s[98:99]
	global_load_dwordx4 v[250:253], v[236:237], off offset:768
	v_lshl_add_u64 v[236:237], v[236:237], 0, s[100:101]
	s_load_dwordx2 s[0:1], s[0:1], 0x68
	v_lshlrev_b32_e32 v16, 16, v118
	v_add_f32_e32 v4, v163, v4
	v_add_f32_e32 v180, v20, v23
	v_cvt_pk_bf16_f32 v107, v18, v19
	s_waitcnt lgkmcnt(0)
	global_load_dword v156, v156, s[0:1] offset:1536
	s_mov_b64 s[0:1], s[80:81]
	s_load_dwordx2 s[28:29], s[0:1], 0x58
	v_cvt_pk_bf16_f32 v106, v21, v22
	v_mul_f32_e32 v181, v4, v16
	s_waitcnt lgkmcnt(0)
	global_load_dwordx4 v[16:19], v139, s[28:29] offset:1584
	global_load_dwordx4 v[20:23], v139, s[28:29] offset:1568
	global_load_dwordx4 v[24:27], v139, s[28:29] offset:1552
	global_load_dwordx4 v[28:31], v139, s[28:29] offset:1536
	v_and_b32_e32 v206, 0xffff0000, v39
	v_fmac_f32_e32 v38, v207, v207
	s_waitcnt vmcnt(19)
	v_lshlrev_b32_e32 v205, 16, v52
	v_fmac_f32_e32 v38, v206, v206
	v_and_b32_e32 v204, 0xffff0000, v52
	v_fmac_f32_e32 v38, v205, v205
	v_lshlrev_b32_e32 v203, 16, v53
	v_fmac_f32_e32 v38, v204, v204
	v_and_b32_e32 v202, 0xffff0000, v53
	v_fmac_f32_e32 v38, v203, v203
	v_lshlrev_b32_e32 v201, 16, v54
	v_fmac_f32_e32 v38, v202, v202
	v_and_b32_e32 v200, 0xffff0000, v54
	v_fmac_f32_e32 v38, v201, v201
	v_lshlrev_b32_e32 v199, 16, v55
	v_fmac_f32_e32 v38, v200, v200
	v_and_b32_e32 v198, 0xffff0000, v55
	v_fmac_f32_e32 v38, v199, v199
	s_waitcnt vmcnt(17)
	v_lshlrev_b32_e32 v197, 16, v60
	v_fmac_f32_e32 v38, v198, v198
	v_and_b32_e32 v196, 0xffff0000, v60
	v_fmac_f32_e32 v38, v197, v197
	v_lshlrev_b32_e32 v195, 16, v61
	v_fmac_f32_e32 v38, v196, v196
	v_and_b32_e32 v194, 0xffff0000, v61
	v_fmac_f32_e32 v38, v195, v195
	v_lshlrev_b32_e32 v193, 16, v62
	v_fmac_f32_e32 v38, v194, v194
	v_and_b32_e32 v192, 0xffff0000, v62
	v_fmac_f32_e32 v38, v193, v193
	v_lshlrev_b32_e32 v191, 16, v63
	v_fmac_f32_e32 v38, v192, v192
	v_add_f32_e32 v189, v163, v5
	v_and_b32_e32 v190, 0xffff0000, v63
	v_fmac_f32_e32 v38, v191, v191
	v_and_b32_e32 v4, 0xffff0000, v32
	v_lshlrev_b32_e32 v5, 16, v32
	v_fmac_f32_e32 v38, v190, v190
	v_pk_mul_f32 v[36:37], v[4:5], v[4:5]
	v_and_b32_e32 v164, 0xffff0000, v33
	v_add_f32_e32 v32, v37, v38
	v_lshlrev_b32_e32 v165, 16, v33
	v_add_f32_e32 v36, v36, v32
	v_pk_mul_f32 v[32:33], v[164:165], v[164:165]
	v_and_b32_e32 v166, 0xffff0000, v34
	v_add_f32_e32 v33, v33, v36
	v_lshlrev_b32_e32 v167, 16, v34
	v_add_f32_e32 v36, v32, v33
	v_pk_mul_f32 v[32:33], v[166:167], v[166:167]
	v_and_b32_e32 v178, 0xffff0000, v35
	v_add_f32_e32 v33, v33, v36
	v_lshlrev_b32_e32 v179, 16, v35
	v_add_f32_e32 v34, v32, v33
	v_pk_mul_f32 v[32:33], v[178:179], v[178:179]
	v_and_b32_e32 v118, 0xffff0000, v118
	v_add_f32_e32 v33, v33, v34
	v_add_f32_e32 v32, v32, v33
	ds_bpermute_b32 v33, v183, v32
	v_lshlrev_b32_e32 v34, 16, v119
	v_add_f32_e32 v6, v163, v6
	v_mul_f32_e32 v118, v189, v118
	v_mul_f32_e32 v189, v6, v34
	s_waitcnt lgkmcnt(0)
	v_add_f32_e32 v6, v32, v33
	global_load_dwordx4 v[32:35], v139, s[28:29] offset:1616
	global_load_dwordx4 v[36:39], v139, s[28:29] offset:1600
	global_load_dwordx4 v[52:55], v139, s[28:29] offset:1648
	global_load_dwordx4 v[60:63], v139, s[28:29] offset:1632
	ds_bpermute_b32 v214, v184, v6
	s_waitcnt lgkmcnt(0)
	s_barrier
; __device__ __forceinline__ float bf_lo(unsigned w) { return __uint_as_float(w << 16); }
; __device__ __forceinline__ float bf_hi(unsigned w) { return __uint_as_float(w & 0xffff0000u); }
; __device__ __forceinline__ bf16 f2bf(float f) { return (bf16)(cvt_pk_nv(f, 0.f) & 0xffffu); }
; __device__ __forceinline__ void gmlp_tile(const Ctx& C, int T, LAS unsigned char* lds, int wave, int lane, int tid) {
;     ...
;         __syncthreads();
;         {
;             float v[32]; float s = 0.f;
; #pragma unroll
;             for (int i = 0; i < 4; ++i) { const v4u w = vraw[i];
;                 v[8 * i + 0] = bf_lo(w.x); v[8 * i + 1] = bf_hi(w.x); v[8 * i + 2] = bf_lo(w.y); v[8 * i + 3] = bf_hi(w.y);
;                 v[8 * i + 4] = bf_lo(w.z); v[8 * i + 5] = bf_hi(w.z); v[8 * i + 6] = bf_lo(w.w); v[8 * i + 7] = bf_hi(w.w); }
;             if (h < 3) {
; #pragma unroll
;                 for (int i = 0; i < 4; ++i) vraw[i] = *(const v4u*)(vsrc + (h + 1) * 128 + 8 * i);
;             }
; #pragma unroll
;             for (int i = 0; i < 32; ++i) s += v[i] * v[i];
;             s += __shfl_xor(s, 1); s += __shfl_xor(s, 2);
;             const float r = rsqrtf(s * (1.f / 128.f) + EPS);
; #pragma unroll
;             for (int i = 0; i < 32; ++i) { v[i] = v[i] * r * gvv[i >> 2][i & 3]; VT[(q * 32 + i) * VT_STRIDE + row] = f2bf(v[i]); }
	v_and_b32_e32 v119, 0xffff0000, v119
	v_add_f32_e32 v6, v6, v214
	v_fmamk_f32 v6, v6, 0x3c000000, v177
	v_mul_f32_e32 v139, 0x4b800000, v6
	v_cmp_gt_f32_e32 vcc, s38, v6
	v_add_f32_e32 v8, v163, v8
	s_nop 0
	v_cndmask_b32_e32 v6, v6, v139, vcc
	v_rsq_f32_e32 v6, v6
	s_nop 0
	v_mul_f32_e32 v139, 0x45800000, v6
	v_cndmask_b32_e32 v6, v6, v139, vcc
	v_mul_f32_e32 v139, v6, v213
	s_waitcnt vmcnt(4)
	ds_write_b128 v254, v[238:241]
	ds_write_b128 v254, v[242:245] offset:1152
	ds_write_b128 v254, v[246:249] offset:2304
	ds_write_b128 v254, v[250:253] offset:3456
	s_waitcnt lgkmcnt(0)
	ds_read_b64 v[122:123], v255
	ds_read_b64 v[120:121], v255 offset:16
	ds_read_b64 v[114:115], v255 offset:32
	ds_read_b64 v[110:111], v255 offset:48
	ds_read_b64 v[108:109], v255 offset:64
	ds_read_b64 v[104:105], v255 offset:80
	ds_read_b64 v[78:79], v255 offset:96
	ds_read_b64 v[76:77], v255 offset:112
	s_waitcnt lgkmcnt(0)
	v_mul_f32_e32 v28, v28, v139
	v_cvt_pk_bf16_f32 v28, v28, v83
	ds_write_b16 v174, v28
	v_mul_f32_e32 v28, v6, v212
	v_mul_f32_e32 v28, v29, v28
	v_cvt_pk_bf16_f32 v28, v28, v83
	ds_write_b16 v174, v28 offset:272
	v_mul_f32_e32 v28, v6, v211
	v_mul_f32_e32 v28, v30, v28
	v_cvt_pk_bf16_f32 v28, v28, v83
	ds_write_b16 v174, v28 offset:544
	v_mul_f32_e32 v28, v6, v210
	v_mul_f32_e32 v28, v31, v28
	v_cvt_pk_bf16_f32 v28, v28, v83
	ds_write_b16 v174, v28 offset:816
	v_mul_f32_e32 v28, v6, v209
	v_mul_f32_e32 v24, v24, v28
	v_cvt_pk_bf16_f32 v24, v24, v83
	ds_write_b16 v174, v24 offset:1088
	v_mul_f32_e32 v24, v6, v208
	v_mul_f32_e32 v24, v25, v24
	v_cvt_pk_bf16_f32 v24, v24, v83
	ds_write_b16 v174, v24 offset:1360
	v_mul_f32_e32 v24, v6, v207
	v_mul_f32_e32 v24, v26, v24
	v_cvt_pk_bf16_f32 v24, v24, v83
	ds_write_b16 v174, v24 offset:1632
	v_mul_f32_e32 v24, v6, v206
	v_mul_f32_e32 v24, v27, v24
	v_cvt_pk_bf16_f32 v24, v24, v83
	ds_write_b16 v174, v24 offset:1904
	v_mul_f32_e32 v24, v6, v205
	v_mul_f32_e32 v20, v20, v24
	v_cvt_pk_bf16_f32 v20, v20, v83
	ds_write_b16 v174, v20 offset:2176
	v_mul_f32_e32 v20, v6, v204
	v_mul_f32_e32 v20, v21, v20
	v_cvt_pk_bf16_f32 v20, v20, v83
	ds_write_b16 v174, v20 offset:2448
	v_mul_f32_e32 v20, v6, v203
	v_mul_f32_e32 v20, v22, v20
	v_cvt_pk_bf16_f32 v20, v20, v83
	ds_write_b16 v174, v20 offset:2720
	v_mul_f32_e32 v20, v6, v202
	v_mul_f32_e32 v20, v23, v20
	v_cvt_pk_bf16_f32 v20, v20, v83
	ds_write_b16 v174, v20 offset:2992
	v_mul_f32_e32 v20, v6, v201
	v_mul_f32_e32 v16, v16, v20
	v_cvt_pk_bf16_f32 v16, v16, v83
	ds_write_b16 v174, v16 offset:3264
	v_mul_f32_e32 v16, v6, v200
	v_mul_f32_e32 v16, v17, v16
	v_cvt_pk_bf16_f32 v16, v16, v83
	ds_write_b16 v174, v16 offset:3536
	v_mul_f32_e32 v16, v6, v199
	v_mul_f32_e32 v16, v18, v16
	v_cvt_pk_bf16_f32 v16, v16, v83
	ds_write_b16 v174, v16 offset:3808
	v_mul_f32_e32 v16, v6, v198
	v_mul_f32_e32 v16, v19, v16
	v_cvt_pk_bf16_f32 v16, v16, v83
	ds_write_b16 v174, v16 offset:4080
	v_mul_f32_e32 v16, v6, v197
	s_waitcnt vmcnt(2)
	v_mul_f32_e32 v16, v36, v16
	v_cvt_pk_bf16_f32 v16, v16, v83
	ds_write_b16 v174, v16 offset:4352
	v_mul_f32_e32 v16, v6, v196
	v_mul_f32_e32 v16, v37, v16
	v_mul_f32_e32 v4, v6, v4
	v_cvt_pk_bf16_f32 v16, v16, v83
	s_waitcnt vmcnt(0)
	v_mul_f32_e32 v4, v61, v4
	ds_write_b16 v174, v16 offset:4624
	v_mul_f32_e32 v16, v6, v195
	v_cvt_pk_bf16_f32 v4, v4, v83
	v_mul_f32_e32 v16, v38, v16
	ds_write_b16 v174, v4 offset:6800
	v_mul_f32_e32 v4, v6, v165
	v_cvt_pk_bf16_f32 v16, v16, v83
	v_mul_f32_e32 v4, v62, v4
	ds_write_b16 v174, v16 offset:4896
	v_mul_f32_e32 v16, v6, v194
	v_cvt_pk_bf16_f32 v4, v4, v83
	v_mul_f32_e32 v16, v39, v16
	ds_write_b16 v174, v4 offset:7072
	v_mul_f32_e32 v4, v6, v164
	v_cvt_pk_bf16_f32 v16, v16, v83
	v_mul_f32_e32 v4, v63, v4
	ds_write_b16 v174, v16 offset:5168
	v_mul_f32_e32 v16, v6, v193
	v_cvt_pk_bf16_f32 v4, v4, v83
	v_mul_f32_e32 v16, v32, v16
	ds_write_b16 v174, v4 offset:7344
	v_mul_f32_e32 v4, v6, v167
	v_cvt_pk_bf16_f32 v16, v16, v83
	v_mul_f32_e32 v4, v52, v4
	ds_write_b16 v174, v16 offset:5440
	v_mul_f32_e32 v16, v6, v192
	v_cvt_pk_bf16_f32 v4, v4, v83
	v_mul_f32_e32 v16, v33, v16
	ds_write_b16 v174, v4 offset:7616
	v_mul_f32_e32 v4, v6, v166
	v_cvt_pk_bf16_f32 v16, v16, v83
	v_mul_f32_e32 v4, v53, v4
	ds_write_b16 v174, v16 offset:5712
	v_mul_f32_e32 v16, v6, v191
	v_cvt_pk_bf16_f32 v4, v4, v83
	v_mul_f32_e32 v16, v34, v16
	ds_write_b16 v174, v4 offset:7888
	v_mul_f32_e32 v4, v6, v179
	v_cvt_pk_bf16_f32 v16, v16, v83
	v_mul_f32_e32 v4, v54, v4
	ds_write_b16 v174, v16 offset:5984
	v_mul_f32_e32 v16, v6, v190
	v_cvt_pk_bf16_f32 v4, v4, v83
	v_mul_f32_e32 v16, v35, v16
	v_mul_f32_e32 v5, v6, v5
	ds_write_b16 v174, v4 offset:8160
	v_mul_f32_e32 v4, v6, v178
	v_cvt_pk_bf16_f32 v16, v16, v83
	v_mul_f32_e32 v5, v60, v5
	v_mul_f32_e32 v4, v55, v4
	ds_write_b16 v174, v16 offset:6256
	v_cvt_pk_bf16_f32 v5, v5, v83
	ds_write_b16 v174, v5 offset:6528
	v_cvt_pk_bf16_f32 v4, v4, v83
	ds_write_b16 v174, v4 offset:8432
	s_waitcnt lgkmcnt(0)
	s_barrier
; __device__ __forceinline__ float bf_lo(unsigned w) { return __uint_as_float(w << 16); }
; __device__ __forceinline__ float bf_hi(unsigned w) { return __uint_as_float(w & 0xffff0000u); }
; #define LAS __attribute__((address_space(3)))
; __device__ __forceinline__ unsigned cvt_pk_nv(float lo, float hi) { unsigned r; asm("v_cvt_pk_bf16_f32 %0, %1, %2" : "=v"(r) : "v"(lo), "v"(hi)); return r; }
; __device__ __forceinline__ void gmlp_tile(const Ctx& C, int T, LAS unsigned char* lds, int wave, int lane, int tid) {
;     ...
; #pragma unroll
;         for (int dbi = 0; dbi < 2; ++dbi) {
;             const int db = 2 * dh + dbi;
;             v16f acc;
; #pragma unroll
;             for (int r = 0; r < 16; ++r) acc[r] = 0.f;
; #pragma unroll
;             for (int ks = 0; ks < 8; ++ks) {
;                 const bfx8 va = *(const LAS bfx8*)(VT + (32 * db + tl) * VT_STRIDE + 16 * ks + 8 * hh);
;                 acc = __builtin_amdgcn_mfma_f32_32x32x16_bf16(va, wf[ks], acc, 0, 0, 0);
;             }
; #pragma unroll
;             for (int rg = 0; rg < 4; ++rg) {
;                 const v2u u2 = uw[dbi][rg];
;                 const float o0 = bf_lo(u2.x) * (acc[4 * rg + 0] + bias), o1 = bf_hi(u2.x) * (acc[4 * rg + 1] + bias);
;                 const float o2 = bf_lo(u2.y) * (acc[4 * rg + 2] + bias), o3 = bf_hi(u2.y) * (acc[4 * rg + 3] + bias);
;                 ssq += (o0 * o0 + o1 * o1) + (o2 * o2 + o3 * o3);
;                 outp[h][dbi][2 * rg] = cvt_pk_nv(o0, o1); outp[h][dbi][2 * rg + 1] = cvt_pk_nv(o2, o3);
;             }
	ds_read_b128 v[16:19], v102
	v_add_f32_e32 v4, v163, v7
	v_mul_f32_e32 v32, v4, v119
	v_mul_f32_e32 v4, v118, v118
	v_mul_f32_e32 v5, v32, v32
	v_fmac_f32_e32 v4, v181, v181
	v_fmac_f32_e32 v5, v189, v189
	v_add_f32_e32 v33, v4, v5
	ds_read_b128 v[4:7], v102 offset:32
	s_waitcnt lgkmcnt(1)
	v_mfma_f32_32x32x16_bf16 v[16:31], v[16:19], v[0:3], 0
	ds_read_b128 v[36:39], v102 offset:64
	v_lshlrev_b32_e32 v34, 16, v116
	v_mul_f32_e32 v34, v8, v34
	v_and_b32_e32 v8, 0xffff0000, v117
	v_add_f32_e32 v33, v33, v180
	ds_read_b128 v[60:63], v102 offset:8768
	v_cvt_pk_bf16_f32 v35, v181, v118
	s_waitcnt lgkmcnt(2)
	v_mfma_f32_32x32x16_bf16 v[16:31], v[4:7], v[72:75], v[16:31]
	v_and_b32_e32 v4, 0xffff0000, v116
	v_add_f32_e32 v5, v163, v9
	v_mul_f32_e32 v52, v5, v4
	v_lshlrev_b32_e32 v4, 16, v117
	v_add_f32_e32 v5, v163, v10
	v_mul_f32_e32 v53, v5, v4
	ds_read_b128 v[4:7], v102 offset:96
	s_waitcnt lgkmcnt(2)
	v_mfma_f32_32x32x16_bf16 v[16:31], v[36:39], v[68:71], v[16:31]
	v_add_f32_e32 v9, v163, v11
	v_mul_f32_e32 v37, v9, v8
	ds_read_b128 v[8:11], v102 offset:128
	v_mul_f32_e32 v36, v52, v52
	v_mul_f32_e32 v38, v37, v37
	v_fmac_f32_e32 v36, v34, v34
	v_fmac_f32_e32 v38, v53, v53
	s_waitcnt lgkmcnt(1)
	v_mfma_f32_32x32x16_bf16 v[16:31], v[4:7], v[64:67], v[16:31]
	v_add_f32_e32 v4, v36, v38
	v_add_f32_e32 v38, v4, v33
	ds_read_b128 v[4:7], v102 offset:160
	v_cvt_pk_bf16_f32 v36, v34, v52
	v_lshlrev_b32_e32 v34, 16, v112
	v_cvt_pk_bf16_f32 v33, v53, v37
	ds_read_b128 v[52:55], v102 offset:8736
	s_waitcnt lgkmcnt(2)
	v_mfma_f32_32x32x16_bf16 v[16:31], v[8:11], v[56:59], v[16:31]
	v_add_f32_e32 v8, v163, v12
	v_mul_f32_e32 v12, v8, v34
	v_and_b32_e32 v8, 0xffff0000, v112
	v_add_f32_e32 v9, v163, v13
	v_mul_f32_e32 v13, v9, v8
	ds_read_b128 v[8:11], v102 offset:192
	v_lshlrev_b32_e32 v34, 16, v113
	s_waitcnt lgkmcnt(2)
	v_mfma_f32_32x32x16_bf16 v[16:31], v[4:7], v[48:51], v[16:31]
	v_add_f32_e32 v4, v163, v14
	v_mul_f32_e32 v14, v4, v34
	v_and_b32_e32 v4, 0xffff0000, v113
	v_add_f32_e32 v5, v163, v15
	v_mul_f32_e32 v15, v5, v4
	ds_read_b128 v[4:7], v102 offset:224
	v_mul_f32_e32 v34, v13, v13
	s_waitcnt lgkmcnt(1)
	v_mfma_f32_32x32x16_bf16 v[16:31], v[8:11], v[44:47], v[16:31]
	v_mul_f32_e32 v8, v15, v15
	v_fmac_f32_e32 v34, v12, v12
	v_fmac_f32_e32 v8, v14, v14
	v_add_f32_e32 v8, v34, v8
	v_add_f32_e32 v8, v8, v38
	v_cvt_pk_bf16_f32 v37, v12, v13
	v_cvt_pk_bf16_f32 v34, v14, v15
	s_waitcnt lgkmcnt(0)
	v_mfma_f32_32x32x16_bf16 v[16:31], v[4:7], v[40:43], v[16:31]
	v_lshlrev_b32_e32 v4, 16, v122
	v_and_b32_e32 v39, 0xffff0000, v115
	v_cvt_pk_bf16_f32 v32, v189, v32
	s_nop 9
	v_add_f32_e32 v5, v156, v16
	v_mul_f32_e32 v4, v5, v4
	v_and_b32_e32 v5, 0xffff0000, v122
	v_add_f32_e32 v6, v156, v17
	v_mul_f32_e32 v5, v6, v5
	v_lshlrev_b32_e32 v6, 16, v123
	v_add_f32_e32 v7, v156, v18
	v_mul_f32_e32 v6, v7, v6
	v_and_b32_e32 v7, 0xffff0000, v123
	v_add_f32_e32 v9, v156, v19
	v_mul_f32_e32 v7, v9, v7
	v_mul_f32_e32 v9, v5, v5
	v_fmac_f32_e32 v9, v4, v4
	v_cvt_pk_bf16_f32 v17, v4, v5
	v_lshlrev_b32_e32 v4, 16, v120
	v_add_f32_e32 v5, v156, v20
	v_mul_f32_e32 v19, v5, v4
	v_and_b32_e32 v4, 0xffff0000, v120
	v_add_f32_e32 v5, v156, v21
	v_mul_f32_e32 v10, v7, v7
	v_mul_f32_e32 v20, v5, v4
	v_lshlrev_b32_e32 v4, 16, v121
	v_add_f32_e32 v5, v156, v22
	v_fmac_f32_e32 v10, v6, v6
	v_cvt_pk_bf16_f32 v16, v6, v7
	v_mul_f32_e32 v21, v5, v4
	ds_read_b128 v[4:7], v102 offset:8704
	v_add_f32_e32 v9, v9, v10
	v_add_f32_e32 v18, v8, v9
	v_and_b32_e32 v8, 0xffff0000, v121
	v_add_f32_e32 v9, v156, v23
	v_mul_f32_e32 v22, v9, v8
	v_mul_f32_e32 v8, v20, v20
	v_mul_f32_e32 v9, v22, v22
	v_fmac_f32_e32 v8, v19, v19
	v_fmac_f32_e32 v9, v21, v21
	v_add_f32_e32 v23, v8, v9
	s_waitcnt lgkmcnt(0)
	v_mfma_f32_32x32x16_bf16 v[0:15], v[4:7], v[0:3], 0
	v_add_f32_e32 v38, v23, v18
	v_cvt_pk_bf16_f32 v20, v19, v20
	v_cvt_pk_bf16_f32 v18, v21, v22
	v_lshlrev_b32_e32 v19, 16, v114
	v_add_f32_e32 v21, v156, v24
	v_mul_f32_e32 v19, v21, v19
	v_and_b32_e32 v21, 0xffff0000, v114
	v_mfma_f32_32x32x16_bf16 v[0:15], v[52:55], v[72:75], v[0:15]
	v_add_f32_e32 v22, v156, v25
	v_mul_f32_e32 v21, v22, v21
	v_lshlrev_b32_e32 v22, 16, v115
	v_add_f32_e32 v23, v156, v26
	v_mul_f32_e32 v26, v23, v22
	ds_read_b128 v[22:25], v102 offset:8800
	ds_read_b128 v[52:55], v102 offset:8832
	v_mfma_f32_32x32x16_bf16 v[0:15], v[60:63], v[68:71], v[0:15]
	v_add_f32_e32 v27, v156, v27
	v_mul_f32_e32 v27, v27, v39
	v_mul_f32_e32 v39, v21, v21
	v_mul_f32_e32 v60, v27, v27
	v_fmac_f32_e32 v39, v19, v19
	v_fmac_f32_e32 v60, v26, v26
	v_cvt_pk_bf16_f32 v21, v19, v21
	s_waitcnt lgkmcnt(1)
; __device__ __forceinline__ float bf_lo(unsigned w) { return __uint_as_float(w << 16); }
; __device__ __forceinline__ float bf_hi(unsigned w) { return __uint_as_float(w & 0xffff0000u); }
; __device__ __forceinline__ unsigned cvt_pk_nv(float lo, float hi) { unsigned r; asm("v_cvt_pk_bf16_f32 %0, %1, %2" : "=v"(r) : "v"(lo), "v"(hi)); return r; }
; __device__ __forceinline__ void gmlp_tile(const Ctx& C, int T, LAS unsigned char* lds, int wave, int lane, int tid) {
;     ...
;                 acc = __builtin_amdgcn_mfma_f32_32x32x16_bf16(va, wf[ks], acc, 0, 0, 0);
;             }
; #pragma unroll
;             for (int rg = 0; rg < 4; ++rg) {
;                 const v2u u2 = uw[dbi][rg];
;                 const float o0 = bf_lo(u2.x) * (acc[4 * rg + 0] + bias), o1 = bf_hi(u2.x) * (acc[4 * rg + 1] + bias);
;                 const float o2 = bf_lo(u2.y) * (acc[4 * rg + 2] + bias), o3 = bf_hi(u2.y) * (acc[4 * rg + 3] + bias);
;                 ssq += (o0 * o0 + o1 * o1) + (o2 * o2 + o3 * o3);
;                 outp[h][dbi][2 * rg] = cvt_pk_nv(o0, o1); outp[h][dbi][2 * rg + 1] = cvt_pk_nv(o2, o3);
;             }
;         }
;     }
;     ssq += __shfl_xor(ssq, 32);
;     if (hh == 0) SSQ[t * 2 + dh] = ssq;
	v_mfma_f32_32x32x16_bf16 v[0:15], v[22:25], v[64:67], v[0:15]
	v_add_f32_e32 v22, v39, v60
	v_add_f32_e32 v38, v22, v38
	ds_read_b128 v[22:25], v102 offset:8864
	v_cvt_pk_bf16_f32 v19, v26, v27
	v_lshlrev_b32_e32 v26, 16, v110
	v_add_f32_e32 v27, v156, v28
	v_mul_f32_e32 v39, v27, v26
	s_waitcnt lgkmcnt(1)
	v_mfma_f32_32x32x16_bf16 v[0:15], v[52:55], v[56:59], v[0:15]
	v_and_b32_e32 v26, 0xffff0000, v110
	v_add_f32_e32 v27, v156, v29
	v_mul_f32_e32 v52, v27, v26
	ds_read_b128 v[26:29], v102 offset:8896
	v_lshlrev_b32_e32 v53, 16, v111
	s_waitcnt lgkmcnt(1)
	v_mfma_f32_32x32x16_bf16 v[0:15], v[22:25], v[48:51], v[0:15]
	ds_read_b128 v[48:51], v102 offset:8928
	v_and_b32_e32 v23, 0xffff0000, v111
	v_add_f32_e32 v24, v156, v31
	v_add_f32_e32 v22, v156, v30
	v_mul_f32_e32 v24, v24, v23
	v_mul_f32_e32 v22, v22, v53
	v_mul_f32_e32 v25, v24, v24
	s_waitcnt lgkmcnt(1)
	v_mfma_f32_32x32x16_bf16 v[0:15], v[26:29], v[44:47], v[0:15]
	v_fmac_f32_e32 v25, v22, v22
	v_cvt_pk_bf16_f32 v22, v22, v24
	v_lshlrev_b32_e32 v24, 16, v108
	v_mul_f32_e32 v23, v52, v52
	v_fmac_f32_e32 v23, v39, v39
	v_add_f32_e32 v23, v23, v25
	v_add_f32_e32 v25, v23, v38
	s_waitcnt lgkmcnt(0)
	v_mfma_f32_32x32x16_bf16 v[0:15], v[48:51], v[40:43], v[0:15]
	v_cvt_pk_bf16_f32 v23, v39, v52
	s_nop 11
	v_add_f32_e32 v0, v156, v0
	v_mul_f32_e32 v0, v0, v24
	v_and_b32_e32 v24, 0xffff0000, v108
	v_add_f32_e32 v1, v156, v1
	v_mul_f32_e32 v1, v1, v24
	v_lshlrev_b32_e32 v24, 16, v109
	v_add_f32_e32 v2, v156, v2
	v_mul_f32_e32 v2, v2, v24
	v_and_b32_e32 v24, 0xffff0000, v109
	v_add_f32_e32 v3, v156, v3
	v_mul_f32_e32 v24, v3, v24
	v_mul_f32_e32 v3, v1, v1
	v_mul_f32_e32 v26, v24, v24
	v_fmac_f32_e32 v3, v0, v0
	v_fmac_f32_e32 v26, v2, v2
	v_add_f32_e32 v3, v3, v26
	v_add_f32_e32 v25, v25, v3
	v_cvt_pk_bf16_f32 v3, v0, v1
	v_lshlrev_b32_e32 v0, 16, v104
	v_add_f32_e32 v1, v156, v4
	v_mul_f32_e32 v0, v1, v0
	v_and_b32_e32 v1, 0xffff0000, v104
	v_add_f32_e32 v4, v156, v5
	v_mul_f32_e32 v1, v4, v1
	v_lshlrev_b32_e32 v4, 16, v105
	v_add_f32_e32 v5, v156, v6
	v_mul_f32_e32 v4, v5, v4
	v_and_b32_e32 v5, 0xffff0000, v105
	v_add_f32_e32 v6, v156, v7
	v_mul_f32_e32 v6, v6, v5
	v_mul_f32_e32 v5, v1, v1
	v_mul_f32_e32 v7, v6, v6
	v_fmac_f32_e32 v5, v0, v0
	v_fmac_f32_e32 v7, v4, v4
	v_add_f32_e32 v5, v5, v7
	v_add_f32_e32 v7, v5, v25
	v_cvt_pk_bf16_f32 v5, v0, v1
	v_lshlrev_b32_e32 v0, 16, v78
	v_add_f32_e32 v1, v156, v8
	v_cvt_pk_bf16_f32 v4, v4, v6
	v_mul_f32_e32 v0, v1, v0
	v_and_b32_e32 v1, 0xffff0000, v78
	v_add_f32_e32 v6, v156, v9
	v_mul_f32_e32 v1, v6, v1
	v_lshlrev_b32_e32 v6, 16, v79
	v_add_f32_e32 v8, v156, v10
	v_mul_f32_e32 v8, v8, v6
	v_and_b32_e32 v6, 0xffff0000, v79
	v_add_f32_e32 v9, v156, v11
	v_mul_f32_e32 v9, v9, v6
	v_mul_f32_e32 v6, v1, v1
	v_mul_f32_e32 v10, v9, v9
	v_fmac_f32_e32 v6, v0, v0
	v_fmac_f32_e32 v10, v8, v8
	v_add_f32_e32 v6, v6, v10
	v_add_f32_e32 v7, v6, v7
	v_cvt_pk_bf16_f32 v6, v0, v1
	v_lshlrev_b32_e32 v0, 16, v76
	v_add_f32_e32 v1, v156, v12
	v_mul_f32_e32 v0, v1, v0
	v_and_b32_e32 v1, 0xffff0000, v76
	v_add_f32_e32 v10, v156, v13
	v_mul_f32_e32 v11, v10, v1
	v_lshlrev_b32_e32 v1, 16, v77
	v_add_f32_e32 v10, v156, v14
	v_mul_f32_e32 v12, v10, v1
	v_and_b32_e32 v1, 0xffff0000, v77
	v_add_f32_e32 v10, v156, v15
	v_mul_f32_e32 v13, v10, v1
	v_mul_f32_e32 v1, v11, v11
	v_mul_f32_e32 v10, v13, v13
	v_fmac_f32_e32 v1, v0, v0
	v_fmac_f32_e32 v10, v12, v12
	v_add_f32_e32 v1, v1, v10
	v_add_f32_e32 v1, v1, v7
	ds_bpermute_b32 v10, v188, v1
	v_cvt_pk_bf16_f32 v9, v8, v9
	v_cvt_pk_bf16_f32 v8, v0, v11
	v_lshlrev_b32_e32 v0, 3, v132
	v_cvt_pk_bf16_f32 v2, v2, v24
	v_cvt_pk_bf16_f32 v7, v12, v13
	s_and_saveexec_b64 s[28:29], s[8:9]
	s_cbranch_execz .LBB0_601
	s_lshl_b32 s0, s13, 2
	s_add_i32 s0, s0, 0
	s_waitcnt lgkmcnt(0)
	v_add_f32_e32 v1, v1, v10
	v_add_u32_e32 v10, s0, v0
	ds_write_b32 v10, v1 offset:34816
